# P3 loop: both tokens share one cross-row reduction + one erf-gelu evaluation (rows 0,2 / 1,3), grid barrier: waiters poll the top generation word; N2 v_max3 row max
# speedup vs baseline: 1.0292x; 1.0094x over previous
; __device__ __forceinline__ unsigned xb_ld(unsigned* p)              { return __hip_atomic_load(p, __ATOMIC_RELAXED, __HIP_MEMORY_SCOPE_AGENT); }
; __device__ __forceinline__ unsigned xb_add(unsigned* p, unsigned v) { return __hip_atomic_fetch_add(p, v, __ATOMIC_RELAXED, __HIP_MEMORY_SCOPE_AGENT); }
; #define XB_SPIN(cond, bar) do { unsigned _sp = 0; while (cond) { __builtin_amdgcn_s_sleep(1); \
;     if ((++_sp & 255u) == 0u) { if (xb_ld(&(bar)[XB_TMO])) break; if (_sp > XB_SPIN_CAP) { atomicAdd(&(bar)[XB_TMO], 1u); break; } } } } while (0)
; __device__ __forceinline__ void xcd_barrier(const XcdBarrier& b) {
;     ...
;         const unsigned old = xb_add(&bar[XB_XSUB(b.x)], 1u);
;         const unsigned gen = old / nloc;
;         if (old + 1u == (gen + 1u) * nloc) {
;             __builtin_amdgcn_fence(__ATOMIC_RELEASE, "agent");
;             asm volatile("s_waitcnt vmcnt(0)" ::: "memory");
;             const unsigned og = xb_add(&bar[XB_TOP], 1u);
;             const unsigned tg = og / nx;
;             if (og + 1u == (tg + 1u) * nx) xb_add(&bar[XB_TOPGEN], 1u);
;             else XB_SPIN(xb_ld(&bar[XB_TOPGEN]) == tg, bar);
;             __builtin_amdgcn_fence(__ATOMIC_ACQUIRE, "agent");
;             xb_add(&bar[XB_XGEN(b.x)], 1u);
;             asm volatile("s_waitcnt vmcnt(0)" ::: "memory");
;         } else {
;             XB_SPIN(xb_ld(&bar[XB_XGEN(b.x)]) == gen, bar);
;             __builtin_amdgcn_fence(__ATOMIC_ACQUIRE, "agent");
;             asm volatile("s_waitcnt vmcnt(0)" ::: "memory");
;         }
.LBB0_200:
	s_or_b64 exec, exec, s[10:11]
	v_cvt_f32_u32_e32 v4, v2
	s_waitcnt vmcnt(0)
	v_readfirstlane_b32 s0, v3
	v_sub_u32_e32 v3, 0, v2
	v_rcp_iflag_f32_e32 v4, v4
	v_add_u32_e32 v5, s0, v1
	v_mul_f32_e32 v4, 0x4f7ffffe, v4
	v_cvt_u32_f32_e32 v4, v4
	v_mul_lo_u32 v1, v3, v4
	v_mul_hi_u32 v1, v4, v1
	v_add_u32_e32 v1, v4, v1
	v_mul_hi_u32 v1, v5, v1
	v_mul_lo_u32 v3, v1, v2
	v_sub_u32_e32 v3, v5, v3
	v_add_u32_e32 v4, 1, v1
	v_cmp_ge_u32_e32 vcc, v3, v2
	s_nop 1
	v_cndmask_b32_e32 v1, v1, v4, vcc
	v_sub_u32_e32 v4, v3, v2
	v_cndmask_b32_e32 v3, v3, v4, vcc
	v_add_u32_e32 v4, 1, v1
	v_cmp_ge_u32_e32 vcc, v3, v2
	v_add_u32_e32 v3, 1, v5
	s_nop 0
	v_cndmask_b32_e32 v1, v1, v4, vcc
	v_mul_lo_u32 v4, v2, v1
	v_add_u32_e32 v2, v4, v2
	v_cmp_ne_u32_e32 vcc, v3, v2
	s_and_saveexec_b64 s[0:1], vcc
	s_xor_b64 s[8:9], exec, s[0:1]
	s_cbranch_execz .LBB0_214
	s_waitcnt lgkmcnt(0)
	v_mov_b32_e32 v0, 0x3100
	global_load_dword v0, v0, s[78:79] offset:1024 sc1
	s_add_u32 s14, s78, 0x3500
	s_addc_u32 s15, s79, 0
	s_waitcnt vmcnt(0)
	v_cmp_eq_u32_e32 vcc, v0, v1
	s_and_saveexec_b64 s[10:11], vcc
	s_cbranch_execz .LBB0_213
	s_mov_b32 s0, 1
	s_mov_b64 s[16:17], 0
	v_mov_b32_e32 v0, 0
	s_branch .LBB0_204

; __device__ __forceinline__ unsigned xb_ld(unsigned* p)              { return __hip_atomic_load(p, __ATOMIC_RELAXED, __HIP_MEMORY_SCOPE_AGENT); }
; __device__ __forceinline__ unsigned xb_add(unsigned* p, unsigned v) { return __hip_atomic_fetch_add(p, v, __ATOMIC_RELAXED, __HIP_MEMORY_SCOPE_AGENT); }
; #define XB_SPIN(cond, bar) do { unsigned _sp = 0; while (cond) { __builtin_amdgcn_s_sleep(1); \
;     if ((++_sp & 255u) == 0u) { if (xb_ld(&(bar)[XB_TMO])) break; if (_sp > XB_SPIN_CAP) { atomicAdd(&(bar)[XB_TMO], 1u); break; } } } } while (0)
; __device__ __forceinline__ void xcd_barrier(const XcdBarrier& b) {
;     ...
;         const unsigned old = xb_add(&bar[XB_XSUB(b.x)], 1u);
;         const unsigned gen = old / nloc;
;         if (old + 1u == (gen + 1u) * nloc) {
;             __builtin_amdgcn_fence(__ATOMIC_RELEASE, "agent");
;             asm volatile("s_waitcnt vmcnt(0)" ::: "memory");
;             const unsigned og = xb_add(&bar[XB_TOP], 1u);
;             const unsigned tg = og / nx;
;             if (og + 1u == (tg + 1u) * nx) xb_add(&bar[XB_TOPGEN], 1u);
;             else XB_SPIN(xb_ld(&bar[XB_TOPGEN]) == tg, bar);
;             __builtin_amdgcn_fence(__ATOMIC_ACQUIRE, "agent");
;             xb_add(&bar[XB_XGEN(b.x)], 1u);
;             asm volatile("s_waitcnt vmcnt(0)" ::: "memory");
;         } else {
;             XB_SPIN(xb_ld(&bar[XB_XGEN(b.x)]) == gen, bar);
;             __builtin_amdgcn_fence(__ATOMIC_ACQUIRE, "agent");
;             asm volatile("s_waitcnt vmcnt(0)" ::: "memory");
;         }
.LBB0_557:
	s_or_b64 exec, exec, s[10:11]
	v_cvt_f32_u32_e32 v4, v2
	s_waitcnt vmcnt(0)
	v_readfirstlane_b32 s0, v3
	v_sub_u32_e32 v3, 0, v2
	v_rcp_iflag_f32_e32 v4, v4
	v_add_u32_e32 v5, s0, v1
	v_mul_f32_e32 v4, 0x4f7ffffe, v4
	v_cvt_u32_f32_e32 v4, v4
	v_mul_lo_u32 v1, v3, v4
	v_mul_hi_u32 v1, v4, v1
	v_add_u32_e32 v1, v4, v1
	v_mul_hi_u32 v1, v5, v1
	v_mul_lo_u32 v3, v1, v2
	v_sub_u32_e32 v3, v5, v3
	v_add_u32_e32 v4, 1, v1
	v_cmp_ge_u32_e32 vcc, v3, v2
	s_nop 1
	v_cndmask_b32_e32 v1, v1, v4, vcc
	v_sub_u32_e32 v4, v3, v2
	v_cndmask_b32_e32 v3, v3, v4, vcc
	v_add_u32_e32 v4, 1, v1
	v_cmp_ge_u32_e32 vcc, v3, v2
	v_add_u32_e32 v3, 1, v5
	s_nop 0
	v_cndmask_b32_e32 v1, v1, v4, vcc
	v_mul_lo_u32 v4, v2, v1
	v_add_u32_e32 v2, v4, v2
	v_cmp_ne_u32_e32 vcc, v3, v2
	s_and_saveexec_b64 s[0:1], vcc
	s_xor_b64 s[8:9], exec, s[0:1]
	s_cbranch_execz .LBB0_571
	s_waitcnt lgkmcnt(0)
	v_mov_b32_e32 v0, 0x3100
	global_load_dword v0, v0, s[78:79] offset:1024 sc1
	s_add_u32 s12, s78, 0x3500
	s_addc_u32 s13, s79, 0
	s_waitcnt vmcnt(0)
	v_cmp_eq_u32_e32 vcc, v0, v1
	s_and_saveexec_b64 s[10:11], vcc
	s_cbranch_execz .LBB0_570
	s_mov_b32 s0, 1
	s_mov_b64 s[14:15], 0
	v_mov_b32_e32 v0, 0
	s_branch .LBB0_561

; __device__ __forceinline__ float bf_lo(unsigned u) { return __uint_as_float(u << 16); }
; __device__ __forceinline__ float bf_hi(unsigned u) { return __uint_as_float(u & 0xffff0000u); }
; __device__ __forceinline__ void p3_token(const Params& p, int tok, int lane, unsigned* rec, float& sh, int& hs8) {
;     const bf16_t* H = (const bf16_t*)(p.ws + OFF_H);
;     const int* eidx = (const int*)(p.ws + OFF_EIDX);
;     const float* gwp = (const float*)(p.ws + OFF_GW);
;     {
;         const u32x4 a = *(const u32x4*)(H + (size_t)tok * DM + lane * 16), b = *(const u32x4*)(H + (size_t)tok * DM + lane * 16 + 8);
;         const unsigned hw[8] = {a.x, a.y, a.z, a.w, b.x, b.y, b.z, b.w};
;         float hv[16];
;         float mx = 0.f;
; #pragma unroll
;         for (int i = 0; i < 8; i++) { hv[2 * i] = bf_lo(hw[i]); hv[2 * i + 1] = bf_hi(hw[i]); mx = fmaxf(mx, fmaxf(fabsf(hv[2 * i]), fabsf(hv[2 * i + 1]))); }
;         mx = wave_max(mx);
;         const float inv = mx > 0.f ? 119.f / mx : 0.f;
;         sh = mx * (1.f / 119.f);
; __device__ void phaseP3(const Params& p, float* dstp, char* lds) {
;     ...
;     const int ul = ((lane & 1) << 1) | ((lane >> 1) & 1);
.LBB0_1040:
	s_or_b64 exec, exec, s[4:5]
	v_readfirstlane_b32 s0, v158
	v_readlane_b32 s1, v222, 0
	s_lshr_b32 s0, s0, 5
	v_mov_b32_e32 v1, v158
	s_lshl_b32 s1, s1, 4
	s_and_b32 s0, s0, 0x7fffff8
	s_waitcnt lgkmcnt(0)
	s_barrier
	s_add_i32 s0, s0, s1
	v_bfe_u32 v0, v1, 6, 2
	v_lshl_or_b32 v8, v0, 1, s0
	s_movk_i32 s0, 0x4000
	v_cmp_gt_i32_e32 vcc, s0, v8
	s_and_saveexec_b64 s[0:1], vcc
	s_cbranch_execz .LBB0_1077
	s_movk_i32 s8, 0x1400
	v_mov_b32_e32 v2, s33
	v_mad_u32_u24 v11, v0, s8, v2
	v_and_b32_e32 v2, 64, v159
	v_add_u32_e32 v2, 64, v2
	v_xor_b32_e32 v3, 32, v159
	v_cmp_lt_i32_e32 vcc, v3, v2
	s_load_dwordx4 s[20:23], s[80:81], 0xd0
	s_load_dwordx2 s[4:5], s[80:81], 0x38
	v_cndmask_b32_e32 v3, v159, v3, vcc
	v_lshlrev_b32_e32 v112, 2, v3
	v_xor_b32_e32 v3, 16, v159
	v_cmp_lt_i32_e32 vcc, v3, v2
	v_and_b32_e32 v10, 63, v1
	v_mov_b32_e32 v13, 0
	v_cndmask_b32_e32 v3, v159, v3, vcc
	v_lshlrev_b32_e32 v113, 2, v3
	v_xor_b32_e32 v3, 8, v159
	v_cmp_lt_i32_e32 vcc, v3, v2
	v_lshlrev_b32_e32 v12, 4, v10
	s_mov_b64 s[0:1], 0x9c00000
	v_cndmask_b32_e32 v3, v159, v3, vcc
	v_lshlrev_b32_e32 v114, 2, v3
	v_xor_b32_e32 v3, 4, v159
	v_cmp_lt_i32_e32 vcc, v3, v2
	s_lshl_b32 s36, s72, 4
	v_bfrev_b32_e32 v4, v1
	v_cndmask_b32_e32 v3, v159, v3, vcc
	v_lshlrev_b32_e32 v115, 2, v3
	v_xor_b32_e32 v3, 2, v159
	v_cmp_lt_i32_e32 vcc, v3, v2
	s_waitcnt vmcnt(3) lgkmcnt(0)
	v_lshl_add_u64 v[18:19], s[20:21], 0, v[12:13]
	s_add_u32 s20, s22, 0xdd00000
	v_cndmask_b32_e32 v3, v159, v3, vcc
	v_lshlrev_b32_e32 v116, 2, v3
	v_xor_b32_e32 v3, 1, v159
	v_cmp_lt_i32_e32 vcc, v3, v2
	s_addc_u32 s21, s23, 0
	v_mov_b32_e32 v5, v13
	v_cndmask_b32_e32 v2, v159, v3, vcc
	v_lshlrev_b32_e32 v117, 2, v2
	v_lshlrev_b32_e32 v2, 3, v10
	v_mov_b32_e32 v3, v13
	v_lshl_add_u64 v[2:3], s[22:23], 0, v[2:3]
	v_lshl_add_u64 v[14:15], v[2:3], 0, s[0:1]
	s_mov_b64 s[0:1], 0xac00000
	v_lshl_add_u64 v[16:17], v[2:3], 0, s[0:1]
	v_and_b32_e32 v2, 1, v1
	v_lshrrev_b32_e32 v3, 28, v4
	v_cmp_eq_u32_e64 s[0:1], 0, v2
	v_lshlrev_b32_e32 v2, 6, v10
	v_and_b32_e32 v6, 12, v3
	v_lshlrev_b32_e32 v4, 5, v10
	s_add_u32 s24, s22, 0xe500000
	v_mov_b32_e32 v3, v13
	v_and_b32_e32 v1, 2, v1
	v_add_u32_e32 v118, v11, v2
	v_lshl_add_u64 v[4:5], s[22:23], 0, v[4:5]
	s_mov_b64 s[6:7], 0x1c00000
	s_addc_u32 s25, s23, 0
	s_waitcnt vmcnt(1)
	v_lshl_add_u64 v[24:25], s[4:5], 0, v[2:3]
	v_mov_b32_e32 v2, s33
	v_cmp_eq_u32_e64 s[2:3], 0, v1
	v_mul_i32_i24_e32 v1, 0xffffffd0, v10
	v_lshl_add_u64 v[20:21], v[4:5], 0, s[6:7]
	s_add_u32 s26, s22, 0xbc00000
	s_mov_b64 s[6:7], 0xbd00000
	v_mad_u32_u24 v0, v0, s8, v2
	s_movk_i32 s4, 0x210
	v_add_u32_e32 v119, v11, v6
	s_addc_u32 s27, s23, 0
	v_lshl_add_u64 v[22:23], v[4:5], 0, s[6:7]
	v_add3_u32 v120, v0, v6, s4
	v_add_u32_e32 v121, 16, v0
	s_mov_b64 s[28:29], 0
	s_mov_b32 s33, 0x42ee0000
	v_mov_b32_e32 v122, 0x80
	s_movk_i32 s37, 0x800
	v_mov_b32_e32 v123, 0x800
	v_mov_b32_e32 v124, 0x8000
	v_mov_b32_e32 v125, 0x80000
	s_mov_b32 s38, 0x800000
	v_mov_b32_e32 v126, 0x800000
	v_bfrev_b32_e32 v127, 16
	v_add_u32_e32 v128, v118, v1
	s_mov_b32 s39, 0x3e6d3388
	v_mov_b32_e32 v129, 0xbf3a00e3
	v_lshlrev_b32_e32 v26, 2, v12
	s_mov_b64 s[30:31], 0x9000
	s_mov_b32 s40, 0x9000
	v_mov_b32_e32 v130, 0x358637bd
	s_movk_i32 s41, 0x3fff
	s_add_u32 s50, s22, 0x9c00000
	s_addc_u32 s51, s23, 0
	s_add_u32 s52, s22, 0xac00000
	s_addc_u32 s53, s23, 0
	v_lshlrev_b32_e32 v136, 3, v159
	v_and_b32_e32 v138, 16, v159
	v_mov_b32_e32 v137, 0xa00
	v_cmp_ne_u32_e64 s[54:55], 0, v138
	s_nop 1
	v_cndmask_b32_e64 v137, 0, v137, s[54:55]
	v_add_u32_e32 v137, v120, v137
.LBB0_1042:
	v_ashrrev_i32_e32 v9, 31, v8
	s_waitcnt vmcnt(0)
	v_lshlrev_b64 v[28:29], 11, v[8:9]
	v_lshl_add_u64 v[30:31], v[20:21], 0, v[28:29]
	global_load_dwordx4 v[0:3], v[30:31], off
	global_load_dwordx4 v[4:7], v[30:31], off offset:16
	s_waitcnt vmcnt(1)
	v_lshlrev_b32_e32 v12, 16, v0
	v_and_b32_e32 v27, 0xffff0000, v0
	v_lshlrev_b32_e32 v36, 16, v1
	v_and_b32_e32 v37, 0xffff0000, v1
	v_lshlrev_b32_e32 v38, 16, v2
	v_and_b32_e32 v39, 0xffff0000, v2
	v_lshlrev_b32_e32 v40, 16, v3
	v_and_b32_e32 v41, 0xffff0000, v3
	v_max_f32_e64 v0, |v27|, |v27|
	v_max_f32_e64 v1, |v12|, |v12|
	v_max_f32_e64 v2, |v37|, |v37|
	v_max_f32_e64 v3, |v36|, |v36|
	s_waitcnt vmcnt(0)
	v_lshlrev_b32_e32 v42, 16, v4
	v_and_b32_e32 v43, 0xffff0000, v4
	v_lshlrev_b32_e32 v44, 16, v5
	v_and_b32_e32 v5, 0xffff0000, v5
	v_lshlrev_b32_e32 v45, 16, v6
	v_and_b32_e32 v46, 0xffff0000, v6
	v_lshlrev_b32_e32 v47, 16, v7
	v_and_b32_e32 v48, 0xffff0000, v7
	v_max_f32_e64 v4, |v39|, |v39|
	v_max_f32_e64 v6, |v38|, |v38|
	v_max_f32_e64 v7, |v41|, |v41|
	v_max_f32_e64 v30, |v40|, |v40|
	v_max_f32_e32 v0, v1, v0
	v_max_f32_e32 v1, v3, v2
	v_max_f32_e64 v31, |v43|, |v43|
	v_max_f32_e64 v32, |v42|, |v42|
	v_max_f32_e64 v33, |v5|, |v5|
	v_max_f32_e64 v34, |v44|, |v44|
	v_max_f32_e32 v2, v6, v4
	v_max_f32_e32 v3, v30, v7
	v_max3_f32 v0, v0, 0, v1
	v_max_f32_e64 v35, |v46|, |v46|
	v_max_f32_e64 v49, |v45|, |v45|
	v_max_f32_e64 v50, |v48|, |v48|
	v_max_f32_e64 v51, |v47|, |v47|
	v_max_f32_e32 v4, v32, v31
	v_max_f32_e32 v6, v34, v33
	v_max3_f32 v0, v0, v2, v3
	v_max_f32_e32 v7, v49, v35
	v_max_f32_e32 v30, v51, v50
	v_max3_f32 v0, v0, v4, v6
	v_max3_f32 v0, v0, v7, v30
	ds_bpermute_b32 v1, v112, v0
	s_waitcnt lgkmcnt(0)
	v_max_f32_e32 v1, v1, v1
	v_max_f32_e32 v0, v0, v1
	ds_bpermute_b32 v1, v113, v0
	s_waitcnt lgkmcnt(0)
	v_max_f32_e32 v1, v1, v1
	v_max_f32_e32 v0, v0, v1
	ds_bpermute_b32 v1, v114, v0
	s_waitcnt lgkmcnt(0)
	v_max_f32_e32 v1, v1, v1
	v_max_f32_e32 v0, v0, v1
	ds_bpermute_b32 v1, v115, v0
	s_waitcnt lgkmcnt(0)
; __device__ __forceinline__ float bf_lo(unsigned u) { return __uint_as_float(u << 16); }
; __device__ __forceinline__ float bf_hi(unsigned u) { return __uint_as_float(u & 0xffff0000u); }
; __device__ __forceinline__ void p3_token(const Params& p, int tok, int lane, unsigned* rec, float& sh, int& hs8) {
;     ...
;         const u32x4 a = *(const u32x4*)(H + (size_t)tok * DM + lane * 16), b = *(const u32x4*)(H + (size_t)tok * DM + lane * 16 + 8);
;         const unsigned hw[8] = {a.x, a.y, a.z, a.w, b.x, b.y, b.z, b.w};
;         float hv[16];
;         float mx = 0.f;
; #pragma unroll
;         for (int i = 0; i < 8; i++) { hv[2 * i] = bf_lo(hw[i]); hv[2 * i + 1] = bf_hi(hw[i]); mx = fmaxf(mx, fmaxf(fabsf(hv[2 * i]), fabsf(hv[2 * i + 1]))); }
;         mx = wave_max(mx);
;         const float inv = mx > 0.f ? 119.f / mx : 0.f;
;         sh = mx * (1.f / 119.f);
;         unsigned qh[4] = {0u, 0u, 0u, 0u};
; #pragma unroll
;         for (int e = 0; e < 16; e++) {
;             const int qi = (int)rintf(hv[e] * inv);
;             const int hh = (qi + 8) >> 4, hl = qi - 16 * hh;
;             qh[(e >> 3) * 2] |= (unsigned)(hh & 15) << ((e & 7) * 4);
;             qh[(e >> 3) * 2 + 1] |= (unsigned)(hl & 15) << ((e & 7) * 4);
;         }
;         hs8 = 0;
;         *(u32x4*)(rec + 256 + lane * 4) = (u32x4){qh[0], qh[1], qh[2], qh[3]};
;     }
;     const int e0 = eidx[(size_t)tok * 128 + lane], e1 = eidx[(size_t)tok * 128 + 64 + lane];
;     const float g0 = gwp[(size_t)tok * 128 + lane], g1 = gwp[(size_t)tok * 128 + 64 + lane];
;     const int k0 = e0 >> 11, k1 = e1 >> 11;
;     int pos0 = 0, pos1 = 0, base = 0;
; #pragma unroll
;     for (int v = 0; v < 8; v++) {
;         const unsigned long long m0 = __ballot(k0 == v), m1 = __ballot(k1 == v);
;         const int c0 = __popcll(m0);
;         const int r0 = __builtin_amdgcn_mbcnt_hi((unsigned)(m0 >> 32), __builtin_amdgcn_mbcnt_lo((unsigned)m0, 0u));
;         const int r1 = __builtin_amdgcn_mbcnt_hi((unsigned)(m1 >> 32), __builtin_amdgcn_mbcnt_lo((unsigned)m1, 0u));
;         pos0 = (k0 == v) ? base + r0 : pos0;
;         pos1 = (k1 == v) ? base + c0 + r1 : pos1;
;         base += c0 + __popcll(m1);
;     }
	v_max_f32_e32 v1, v1, v1
	v_max_f32_e32 v2, v0, v1
	ds_bpermute_b32 v4, v116, v2
	v_lshlrev_b64 v[0:1], 9, v[8:9]
	v_lshl_or_b32 v0, v10, 2, v0
	v_mov_b32_e32 v3, v1
	v_lshl_add_u64 v[6:7], s[20:21], 0, v[0:1]
	s_waitcnt lgkmcnt(0)
	v_max_f32_e32 v4, v4, v4
	v_max_f32_e32 v4, v2, v4
	ds_bpermute_b32 v49, v117, v4
	v_or_b32_e32 v2, 0x100, v0
	v_lshl_add_u64 v[30:31], s[24:25], 0, v[0:1]
	v_lshl_add_u64 v[32:33], s[20:21], 0, v[2:3]
	v_lshl_add_u64 v[34:35], s[24:25], 0, v[2:3]
	s_waitcnt lgkmcnt(0)
	v_max_f32_e32 v0, v49, v49
	v_max_f32_e32 v0, v4, v0
	global_load_dword v4, v[6:7], off
	global_load_dword v1, v[32:33], off
	global_load_dword v2, v[30:31], off
	global_load_dword v3, v[34:35], off
	v_div_scale_f32 v49, s[4:5], v0, v0, s33
	v_rcp_f32_e32 v50, v49
	v_div_scale_f32 v6, vcc, s33, v0, s33
	v_fma_f32 v7, -v49, v50, 1.0
	v_fmac_f32_e32 v50, v7, v50
	v_mul_f32_e32 v7, v6, v50
	v_fma_f32 v30, -v49, v7, v6
	v_fmac_f32_e32 v7, v30, v50
	v_fma_f32 v6, -v49, v7, v6
	v_div_fmas_f32 v6, v6, v50, v7
	v_div_fixup_f32 v6, v6, v0, s33
	v_cmp_lt_f32_e32 vcc, 0, v0
	s_waitcnt vmcnt(2)
	v_cmp_gt_u32_e64 s[4:5], s37, v1
	v_cndmask_b32_e32 v6, 0, v6, vcc
	v_mul_f32_e32 v7, v6, v12
	v_mul_f32_e32 v12, v6, v27
	v_mul_f32_e32 v27, v6, v36
	v_mul_f32_e32 v30, v6, v37
	v_rndne_f32_e32 v7, v7
	v_rndne_f32_e32 v12, v12
	v_mul_f32_e32 v31, v6, v38
	v_mul_f32_e32 v32, v6, v39
	v_mul_f32_e32 v34, v6, v41
	v_rndne_f32_e32 v27, v27
	v_rndne_f32_e32 v30, v30
	v_cvt_i32_f32_e32 v7, v7
	v_cvt_i32_f32_e32 v12, v12
	v_mul_f32_e32 v33, v6, v40
	v_rndne_f32_e32 v31, v31
	v_rndne_f32_e32 v32, v32
	v_rndne_f32_e32 v34, v34
	v_cvt_i32_f32_e32 v27, v27
	v_cvt_i32_f32_e32 v30, v30
	v_rndne_f32_e32 v33, v33
	v_cvt_i32_f32_e32 v31, v31
	v_cvt_i32_f32_e32 v32, v32
	v_cvt_i32_f32_e32 v34, v34
	v_cvt_i32_f32_e32 v33, v33
	v_add_u32_e32 v36, 8, v7
	v_add_u32_e32 v37, 8, v12
	v_and_b32_e32 v7, 15, v7
	v_lshlrev_b32_e32 v12, 4, v12
	v_lshl_add_u32 v38, v27, 4, v122
	v_lshlrev_b32_e32 v27, 8, v27
	v_lshl_add_u32 v39, v30, 8, v123
	v_lshrrev_b32_e32 v36, 4, v36
	v_and_b32_e32 v37, 0xf0, v37
	v_lshl_add_u32 v40, v31, 12, v124
	v_lshl_add_u32 v41, v32, 16, v125
	v_lshl_add_u32 v49, v34, 24, v127
	v_and_b32_e32 v12, 0xf0, v12
	v_and_b32_e32 v38, 0xf00, v38
	v_and_b32_e32 v27, 0xf00, v27
	v_and_b32_e32 v39, 0xf000, v39
	v_lshl_or_b32 v7, v34, 28, v7
	v_and_or_b32 v34, v36, 15, v37
	v_mul_f32_e32 v35, v6, v42
	v_lshlrev_b32_e32 v30, 12, v30
	v_lshlrev_b32_e32 v31, 16, v31
	v_lshl_add_u32 v42, v33, 20, v126
	v_and_b32_e32 v40, 0xf0000, v40
	v_and_b32_e32 v41, 0xf00000, v41
	v_or3_b32 v7, v7, v12, v27
	v_or3_b32 v12, v34, v38, v39
	v_and_b32_e32 v30, 0xf000, v30
	v_and_b32_e32 v31, 0xf0000, v31
	v_and_b32_e32 v42, 0xf000000, v42
	v_and_b32_e32 v49, 0xf0000000, v49
	v_or3_b32 v12, v12, v40, v41
	v_lshlrev_b32_e32 v32, 20, v32
	v_lshlrev_b32_e32 v33, 24, v33
	v_or3_b32 v7, v7, v30, v31
	v_or3_b32 v30, v12, v42, v49
	v_mul_f32_e32 v12, v6, v43
	v_rndne_f32_e32 v35, v35
	v_and_b32_e32 v32, 0xf00000, v32
	v_and_b32_e32 v33, 0xf000000, v33
	v_rndne_f32_e32 v12, v12
	v_or3_b32 v31, v7, v32, v33
	v_cvt_i32_f32_e32 v7, v35
	v_cvt_i32_f32_e32 v12, v12
	v_mul_f32_e32 v33, v6, v44
	v_mul_f32_e32 v5, v6, v5
	v_rndne_f32_e32 v33, v33
	v_rndne_f32_e32 v5, v5
	v_cvt_i32_f32_e32 v33, v33
	v_cvt_i32_f32_e32 v5, v5
	v_add_u32_e32 v27, 8, v7
	v_add_u32_e32 v32, 8, v12
	v_lshrrev_b32_e32 v27, 4, v27
	v_and_b32_e32 v32, 0xf0, v32
	v_and_or_b32 v27, v27, 15, v32
	v_lshl_add_u32 v32, v33, 4, v122
	v_lshl_add_u32 v34, v5, 8, v123
	v_and_b32_e32 v32, 0xf00, v32
	v_and_b32_e32 v34, 0xf000, v34
	v_mul_f32_e32 v35, v6, v45
	v_or3_b32 v27, v27, v32, v34
	v_mul_f32_e32 v34, v6, v46
	v_rndne_f32_e32 v35, v35
	v_rndne_f32_e32 v34, v34
	v_cvt_i32_f32_e32 v35, v35
	v_cvt_i32_f32_e32 v34, v34
	v_mul_f32_e32 v37, v6, v47
	v_mul_f32_e32 v6, v6, v48
	v_rndne_f32_e32 v37, v37
	v_rndne_f32_e32 v6, v6
	v_cvt_i32_f32_e32 v37, v37
	v_cvt_i32_f32_e32 v6, v6
	v_lshl_add_u32 v32, v35, 12, v124
	v_lshl_add_u32 v36, v34, 16, v125
	v_and_b32_e32 v32, 0xf0000, v32
	v_and_b32_e32 v36, 0xf00000, v36
	v_and_b32_e32 v7, 15, v7
	v_lshlrev_b32_e32 v12, 4, v12
	v_lshlrev_b32_e32 v33, 8, v33
	v_or3_b32 v27, v27, v32, v36
	v_lshlrev_b32_e32 v32, 20, v34
	v_and_b32_e32 v12, 0xf0, v12
	v_and_b32_e32 v33, 0xf00, v33
	v_lshlrev_b32_e32 v5, 12, v5
	v_lshlrev_b32_e32 v35, 16, v35
	v_and_b32_e32 v34, 0xf00000, v32
	v_lshl_add_u32 v32, v37, 20, v126
	v_lshlrev_b32_e32 v36, 24, v37
	v_lshl_add_u32 v37, v6, 24, v127
	v_lshl_or_b32 v6, v6, 28, v7
	v_and_b32_e32 v5, 0xf000, v5
	v_and_b32_e32 v35, 0xf0000, v35
	v_or3_b32 v6, v6, v12, v33
	v_and_b32_e32 v32, 0xf000000, v32
	v_and_b32_e32 v36, 0xf000000, v36
	v_and_b32_e32 v37, 0xf0000000, v37
	v_or3_b32 v5, v6, v5, v35
	v_cmp_gt_u32_e32 vcc, s37, v4
	v_or3_b32 v32, v27, v32, v37
	v_or3_b32 v33, v5, v34, v36
	s_bcnt1_i32_b64 s8, vcc
	v_mov_b32_e32 v5, v13
	ds_write_b128 v128, v[30:33] offset:1024
	s_and_saveexec_b64 s[6:7], s[4:5]
	v_mbcnt_lo_u32_b32 v5, s4, 0
	v_mbcnt_hi_u32_b32 v5, s5, v5
	v_add_u32_e32 v5, s8, v5
	s_or_b64 exec, exec, s[6:7]
	v_ashrrev_i32_e32 v6, 11, v4
	s_bcnt1_i32_b64 s42, s[4:5]
	v_cmp_eq_u32_e64 s[4:5], 1, v6
	v_ashrrev_i32_e32 v7, 11, v1
	s_add_i32 s42, s42, s8
	s_bcnt1_i32_b64 s8, s[4:5]
	v_cmp_eq_u32_e64 s[6:7], 1, v7
	s_add_i32 s43, s42, s8
	s_and_saveexec_b64 s[8:9], s[6:7]
	v_mbcnt_lo_u32_b32 v5, s6, 0
	v_mbcnt_hi_u32_b32 v5, s7, v5
	v_add_u32_e32 v5, s43, v5
	s_or_b64 exec, exec, s[8:9]
	s_bcnt1_i32_b64 s6, s[6:7]
	s_add_i32 s43, s43, s6
	v_cmp_eq_u32_e64 s[6:7], 2, v6
	s_bcnt1_i32_b64 s10, s[6:7]
	v_cmp_eq_u32_e64 s[8:9], 2, v7
	s_add_i32 s44, s43, s10
	s_and_saveexec_b64 s[10:11], s[8:9]
; __device__ __forceinline__ float bf_lo(unsigned u) { return __uint_as_float(u << 16); }
; __device__ __forceinline__ float bf_hi(unsigned u) { return __uint_as_float(u & 0xffff0000u); }
; __device__ __forceinline__ void p3_token(const Params& p, int tok, int lane, unsigned* rec, float& sh, int& hs8) {
;     ...
;         const u32x4 a = *(const u32x4*)(H + (size_t)tok * DM + lane * 16), b = *(const u32x4*)(H + (size_t)tok * DM + lane * 16 + 8);
;         const unsigned hw[8] = {a.x, a.y, a.z, a.w, b.x, b.y, b.z, b.w};
;         float hv[16];
;         float mx = 0.f;
; #pragma unroll
;         for (int i = 0; i < 8; i++) { hv[2 * i] = bf_lo(hw[i]); hv[2 * i + 1] = bf_hi(hw[i]); mx = fmaxf(mx, fmaxf(fabsf(hv[2 * i]), fabsf(hv[2 * i + 1]))); }
;         mx = wave_max(mx);
;     ...
;     const int e0 = eidx[(size_t)tok * 128 + lane], e1 = eidx[(size_t)tok * 128 + 64 + lane];
;     const float g0 = gwp[(size_t)tok * 128 + lane], g1 = gwp[(size_t)tok * 128 + 64 + lane];
;     const int k0 = e0 >> 11, k1 = e1 >> 11;
;     int pos0 = 0, pos1 = 0, base = 0;
; #pragma unroll
;     for (int v = 0; v < 8; v++) {
;         const unsigned long long m0 = __ballot(k0 == v), m1 = __ballot(k1 == v);
;         const int c0 = __popcll(m0);
;         const int r0 = __builtin_amdgcn_mbcnt_hi((unsigned)(m0 >> 32), __builtin_amdgcn_mbcnt_lo((unsigned)m0, 0u));
;         const int r1 = __builtin_amdgcn_mbcnt_hi((unsigned)(m1 >> 32), __builtin_amdgcn_mbcnt_lo((unsigned)m1, 0u));
;         pos0 = (k0 == v) ? base + r0 : pos0;
;         pos1 = (k1 == v) ? base + c0 + r1 : pos1;
;         base += c0 + __popcll(m1);
;     }
;     const float* tsc = (const float*)(p.ws + OFF_UB + 33554432);
;     const f32x2 s0 = *(const f32x2*)(tsc + 2 * e0), s1 = *(const f32x2*)(tsc + 2 * e1);
;     rec[pos0] = (unsigned)e0; rec[pos1] = (unsigned)e1;
;     rec[128 + pos0] = __float_as_uint(g0 * s0[1]); rec[128 + pos1] = __float_as_uint(g1 * s1[1]);
;     rec[512 + pos0] = __float_as_uint(sh * s0[0]); rec[512 + pos1] = __float_as_uint(sh * s1[0]);
	v_mbcnt_lo_u32_b32 v5, s8, 0
	v_mbcnt_hi_u32_b32 v5, s9, v5
	v_add_u32_e32 v5, s44, v5
	s_or_b64 exec, exec, s[10:11]
	s_bcnt1_i32_b64 s8, s[8:9]
	s_add_i32 s44, s44, s8
	v_cmp_eq_u32_e64 s[8:9], 3, v6
	s_bcnt1_i32_b64 s12, s[8:9]
	v_cmp_eq_u32_e64 s[10:11], 3, v7
	s_add_i32 s45, s44, s12
	s_and_saveexec_b64 s[12:13], s[10:11]
	v_mbcnt_lo_u32_b32 v5, s10, 0
	v_mbcnt_hi_u32_b32 v5, s11, v5
	v_add_u32_e32 v5, s45, v5
	s_or_b64 exec, exec, s[12:13]
	s_bcnt1_i32_b64 s10, s[10:11]
	s_add_i32 s45, s45, s10
	v_cmp_eq_u32_e64 s[10:11], 4, v6
	s_bcnt1_i32_b64 s14, s[10:11]
	v_cmp_eq_u32_e64 s[12:13], 4, v7
	s_add_i32 s46, s45, s14
	s_and_saveexec_b64 s[14:15], s[12:13]
	v_mbcnt_lo_u32_b32 v5, s12, 0
	v_mbcnt_hi_u32_b32 v5, s13, v5
	v_add_u32_e32 v5, s46, v5
	s_or_b64 exec, exec, s[14:15]
	s_bcnt1_i32_b64 s12, s[12:13]
	s_add_i32 s46, s46, s12
	v_cmp_eq_u32_e64 s[12:13], 5, v6
	s_bcnt1_i32_b64 s16, s[12:13]
	v_cmp_eq_u32_e64 s[14:15], 5, v7
	s_add_i32 s47, s46, s16
	s_and_saveexec_b64 s[16:17], s[14:15]
	v_mbcnt_lo_u32_b32 v5, s14, 0
	v_mbcnt_hi_u32_b32 v5, s15, v5
	v_add_u32_e32 v5, s47, v5
	s_or_b64 exec, exec, s[16:17]
	s_bcnt1_i32_b64 s14, s[14:15]
	s_add_i32 s47, s47, s14
	v_cmp_eq_u32_e64 s[14:15], 6, v6
	s_bcnt1_i32_b64 s18, s[14:15]
	v_cmp_eq_u32_e64 s[16:17], 6, v7
	s_add_i32 s48, s47, s18
	s_and_saveexec_b64 s[18:19], s[16:17]
	v_mbcnt_lo_u32_b32 v5, s16, 0
	v_mbcnt_hi_u32_b32 v5, s17, v5
	v_add_u32_e32 v5, s48, v5
	s_or_b64 exec, exec, s[18:19]
	s_bcnt1_i32_b64 s16, s[16:17]
	s_add_i32 s48, s48, s16
	v_cmp_eq_u32_e64 s[16:17], 7, v6
	v_cmp_eq_u32_e64 s[18:19], 7, v7
	s_and_saveexec_b64 s[34:35], s[18:19]
	s_bcnt1_i32_b64 s49, s[16:17]
	v_mbcnt_lo_u32_b32 v5, s18, 0
	s_add_i32 s49, s48, s49
	v_mbcnt_hi_u32_b32 v5, s19, v5
	v_add_u32_e32 v5, s49, v5
	s_or_b64 exec, exec, s[34:35]
	v_or_b32_e32 v30, 1, v8
	v_ashrrev_i32_e32 v31, 31, v30
	v_lshlrev_b64 v[32:33], 11, v[30:31]
	v_lshl_add_u64 v[6:7], v[20:21], 0, v[32:33]
	global_load_dwordx4 v[34:37], v[6:7], off
	global_load_dwordx4 v[38:41], v[6:7], off offset:16
	v_mbcnt_lo_u32_b32 v7, s16, 0
	v_lshlrev_b32_e32 v6, 1, v4
	v_mbcnt_lo_u32_b32 v43, s12, 0
	v_lshlrev_b32_e32 v42, 1, v1
	v_mbcnt_hi_u32_b32 v51, s17, v7
	v_ashrrev_i32_e32 v7, 31, v6
	v_mbcnt_lo_u32_b32 v44, s10, 0
	v_mbcnt_lo_u32_b32 v45, s8, 0
	v_mbcnt_hi_u32_b32 v52, s13, v43
	v_ashrrev_i32_e32 v43, 31, v42
	v_lshl_add_u64 v[6:7], v[6:7], 2, s[26:27]
	v_mbcnt_hi_u32_b32 v53, s11, v44
	v_mbcnt_hi_u32_b32 v54, s9, v45
	v_lshl_add_u64 v[42:43], v[42:43], 2, s[26:27]
	global_load_dwordx2 v[44:45], v[6:7], off
	global_load_dwordx2 v[46:47], v[42:43], off
	v_mbcnt_lo_u32_b32 v48, s6, 0
	v_mbcnt_lo_u32_b32 v49, s4, 0
	v_mbcnt_lo_u32_b32 v50, vcc_lo, 0
	v_mbcnt_hi_u32_b32 v6, s7, v48
	v_mbcnt_hi_u32_b32 v7, s5, v49
	v_mbcnt_hi_u32_b32 v42, vcc_hi, v50
	v_add_u32_e32 v43, s48, v51
	v_add_u32_e32 v7, s42, v7
	v_cndmask_b32_e32 v42, 0, v42, vcc
	v_add_u32_e32 v6, s43, v6
	v_cndmask_b32_e64 v7, v42, v7, s[4:5]
	v_cndmask_b32_e64 v6, v7, v6, s[6:7]
	v_mbcnt_lo_u32_b32 v27, s14, 0
	v_mbcnt_hi_u32_b32 v27, s15, v27
	v_add_u32_e32 v27, s47, v27
	v_lshl_add_u32 v5, v5, 2, v11
	v_mul_f32_e32 v12, 0x3c09ae41, v0
	v_mov_b32_e32 v0, 0
	s_waitcnt vmcnt(3)
	v_lshlrev_b32_e32 v48, 16, v34
	v_and_b32_e32 v34, 0xffff0000, v34
	v_lshlrev_b32_e32 v49, 16, v35
	v_and_b32_e32 v35, 0xffff0000, v35
	v_lshlrev_b32_e32 v50, 16, v36
	v_and_b32_e32 v36, 0xffff0000, v36
	v_lshlrev_b32_e32 v51, 16, v37
	v_and_b32_e32 v55, 0xffff0000, v37
	s_waitcnt vmcnt(2)
	v_lshlrev_b32_e32 v56, 16, v38
	v_and_b32_e32 v57, 0xffff0000, v38
	v_lshlrev_b32_e32 v58, 16, v39
	v_and_b32_e32 v59, 0xffff0000, v39
	v_max_f32_e64 v37, |v34|, |v34|
	v_max_f32_e64 v38, |v48|, |v48|
	v_max_f32_e64 v39, |v35|, |v35|
	v_max_f32_e64 v62, |v49|, |v49|
	v_max_f32_e64 v63, |v36|, |v36|
	v_max_f32_e64 v64, |v50|, |v50|
	v_max_f32_e64 v65, |v55|, |v55|
	v_max_f32_e64 v66, |v51|, |v51|
	v_max_f32_e32 v37, v38, v37
	v_max_f32_e32 v38, v62, v39
	v_lshlrev_b32_e32 v60, 16, v40
	v_and_b32_e32 v40, 0xffff0000, v40
	v_lshlrev_b32_e32 v61, 16, v41
	v_and_b32_e32 v41, 0xffff0000, v41
	v_max_f32_e64 v67, |v57|, |v57|
	v_max_f32_e64 v68, |v56|, |v56|
	v_max_f32_e64 v69, |v59|, |v59|
	v_max_f32_e64 v70, |v58|, |v58|
	v_max_f32_e32 v39, v64, v63
	v_max_f32_e32 v62, v66, v65
	v_max3_f32 v37, v37, 0, v38
	v_max_f32_e64 v71, |v40|, |v40|
	v_max_f32_e64 v72, |v60|, |v60|
	v_max_f32_e64 v73, |v41|, |v41|
	v_max_f32_e64 v74, |v61|, |v61|
	v_max_f32_e32 v63, v68, v67
	v_max_f32_e32 v64, v70, v69
	v_max3_f32 v37, v37, v39, v62
	v_max_f32_e32 v65, v72, v71
	v_max_f32_e32 v66, v74, v73
	v_max3_f32 v37, v37, v63, v64
	v_max3_f32 v37, v37, v65, v66
	ds_bpermute_b32 v38, v112, v37
	v_add_u32_e32 v39, s46, v52
	v_add_u32_e32 v52, s45, v53
	v_add_u32_e32 v53, s44, v54
	v_cndmask_b32_e64 v6, v6, v53, s[8:9]
	s_waitcnt lgkmcnt(0)
	v_max_f32_e32 v38, v38, v38
	v_max_f32_e32 v37, v37, v38
	ds_bpermute_b32 v38, v113, v37
	v_cndmask_b32_e64 v6, v6, v52, s[10:11]
	v_cndmask_b32_e64 v6, v6, v39, s[12:13]
	v_cndmask_b32_e64 v6, v6, v27, s[14:15]
	v_cndmask_b32_e64 v6, v6, v43, s[16:17]
	s_waitcnt lgkmcnt(0)
	v_max_f32_e32 v38, v38, v38
	v_max_f32_e32 v37, v37, v38
	ds_bpermute_b32 v38, v114, v37
	v_lshl_add_u32 v6, v6, 2, v11
	ds_write_b32 v6, v4
	ds_write_b32 v5, v1
	s_waitcnt vmcnt(1)
	v_mul_f32_e32 v1, v2, v45
	s_waitcnt lgkmcnt(2)
	v_max_f32_e32 v7, v38, v38
	v_max_f32_e32 v7, v37, v7
	ds_bpermute_b32 v37, v115, v7
	s_waitcnt vmcnt(0)
	v_mul_f32_e32 v2, v3, v47
	v_mul_f32_e32 v3, v12, v44
	ds_write_b32 v6, v1 offset:512
	ds_write_b32 v5, v2 offset:512
	ds_write_b32 v6, v3 offset:2048
	v_mul_f32_e32 v12, v12, v46
	s_waitcnt lgkmcnt(3)
; __device__ __forceinline__ void p3_token(const Params& p, int tok, int lane, unsigned* rec, float& sh, int& hs8) {
;     ...
;         mx = wave_max(mx);
;         const float inv = mx > 0.f ? 119.f / mx : 0.f;
;         sh = mx * (1.f / 119.f);
;         unsigned qh[4] = {0u, 0u, 0u, 0u};
; #pragma unroll
;         for (int e = 0; e < 16; e++) {
;             const int qi = (int)rintf(hv[e] * inv);
;             const int hh = (qi + 8) >> 4, hl = qi - 16 * hh;
;             qh[(e >> 3) * 2] |= (unsigned)(hh & 15) << ((e & 7) * 4);
;             qh[(e >> 3) * 2 + 1] |= (unsigned)(hl & 15) << ((e & 7) * 4);
;         }
;         hs8 = 0;
;         *(u32x4*)(rec + 256 + lane * 4) = (u32x4){qh[0], qh[1], qh[2], qh[3]};
;     }
;     const int e0 = eidx[(size_t)tok * 128 + lane], e1 = eidx[(size_t)tok * 128 + 64 + lane];
;     const float g0 = gwp[(size_t)tok * 128 + lane], g1 = gwp[(size_t)tok * 128 + 64 + lane];
	v_max_f32_e32 v4, v37, v37
	v_max_f32_e32 v4, v7, v4
	ds_bpermute_b32 v7, v116, v4
	ds_write_b32 v5, v12 offset:2048
	s_waitcnt lgkmcnt(1)
	v_max_f32_e32 v7, v7, v7
	v_max_f32_e32 v4, v4, v7
	ds_bpermute_b32 v7, v117, v4
	s_waitcnt lgkmcnt(0)
	v_max_f32_e32 v1, v7, v7
	v_max_f32_e32 v1, v4, v1
	v_div_scale_f32 v2, s[4:5], v1, v1, s33
	v_rcp_f32_e32 v3, v2
	v_div_scale_f32 v4, vcc, s33, v1, s33
	v_fma_f32 v5, -v2, v3, 1.0
	v_fmac_f32_e32 v3, v5, v3
	v_mul_f32_e32 v5, v4, v3
	v_fma_f32 v6, -v2, v5, v4
	v_fmac_f32_e32 v5, v6, v3
	v_fma_f32 v2, -v2, v5, v4
	v_div_fmas_f32 v2, v2, v3, v5
	v_div_fixup_f32 v2, v2, v1, s33
	v_cmp_lt_f32_e32 vcc, 0, v1
	s_nop 1
	v_cndmask_b32_e32 v12, 0, v2, vcc
	v_mul_f32_e32 v2, v12, v48
	v_mul_f32_e32 v3, v12, v34
	v_rndne_f32_e32 v2, v2
	v_rndne_f32_e32 v3, v3
	v_cvt_i32_f32_e32 v2, v2
	v_cvt_i32_f32_e32 v3, v3
	v_mul_f32_e32 v4, v12, v49
	v_mul_f32_e32 v5, v12, v35
	v_rndne_f32_e32 v4, v4
	v_add_u32_e32 v6, 8, v2
	v_and_b32_e32 v27, 15, v2
	v_add_u32_e32 v2, 8, v3
	v_lshlrev_b32_e32 v3, 4, v3
	v_cvt_i32_f32_e32 v4, v4
	v_and_b32_e32 v42, 0xf0, v3
	v_rndne_f32_e32 v3, v5
	v_cvt_i32_f32_e32 v3, v3
	v_lshl_add_u32 v7, v4, 4, v122
	v_lshlrev_b32_e32 v4, 8, v4
	v_lshrrev_b32_e32 v6, 4, v6
	v_and_b32_e32 v2, 0xf0, v2
	v_and_b32_e32 v43, 0xf00, v4
	v_lshl_add_u32 v4, v3, 8, v123
	v_and_or_b32 v2, v6, 15, v2
	v_and_b32_e32 v5, 0xf00, v7
	v_and_b32_e32 v4, 0xf000, v4
	v_mul_f32_e32 v6, v12, v50
	v_rndne_f32_e32 v6, v6
	v_or3_b32 v2, v2, v5, v4
	v_mul_f32_e32 v4, v12, v36
	v_cvt_i32_f32_e32 v6, v6
	v_rndne_f32_e32 v4, v4
	v_cvt_i32_f32_e32 v4, v4
	v_lshlrev_b32_e32 v3, 12, v3
	v_lshlrev_b32_e32 v5, 16, v6
	v_and_b32_e32 v44, 0xf000, v3
	v_lshl_add_u32 v3, v6, 12, v124
	v_and_b32_e32 v45, 0xf0000, v5
	v_lshl_add_u32 v5, v4, 16, v125
	v_and_b32_e32 v3, 0xf0000, v3
	v_and_b32_e32 v5, 0xf00000, v5
	v_or3_b32 v46, v2, v3, v5
	v_lshlrev_b32_e32 v2, 20, v4
	v_and_b32_e32 v47, 0xf00000, v2
	v_mul_f32_e32 v2, v12, v51
	v_rndne_f32_e32 v2, v2
	v_cvt_i32_f32_e32 v48, v2
	v_lshlrev_b64 v[2:3], 9, v[30:31]
	v_lshl_or_b32 v2, v10, 2, v2
	v_lshl_add_u64 v[6:7], s[20:21], 0, v[2:3]
	v_or_b32_e32 v4, 0x100, v2
	v_mov_b32_e32 v5, v3
	v_lshl_add_u64 v[34:35], s[20:21], 0, v[4:5]
	v_lshl_add_u64 v[36:37], s[24:25], 0, v[2:3]
	v_lshl_add_u64 v[38:39], s[24:25], 0, v[4:5]
	global_load_dword v2, v[6:7], off
	global_load_dword v3, v[34:35], off
	global_load_dword v4, v[36:37], off
	global_load_dword v5, v[38:39], off
	v_mul_f32_e32 v7, v12, v55
	v_rndne_f32_e32 v7, v7
	v_cvt_i32_f32_e32 v7, v7
	v_lshlrev_b32_e32 v34, 24, v48
	v_lshl_add_u32 v6, v48, 20, v126
	v_and_b32_e32 v35, 0xf000000, v34
	v_lshl_add_u32 v34, v7, 24, v127
	v_and_b32_e32 v6, 0xf000000, v6
	v_and_b32_e32 v34, 0xf0000000, v34
	v_or3_b32 v34, v46, v6, v34
	v_lshl_or_b32 v6, v7, 28, v27
	v_or3_b32 v6, v6, v42, v43
	v_or3_b32 v6, v6, v44, v45
	v_or3_b32 v35, v6, v47, v35
	v_mul_f32_e32 v6, v12, v56
	v_mul_f32_e32 v7, v12, v57
	v_rndne_f32_e32 v6, v6
	v_rndne_f32_e32 v7, v7
	v_cvt_i32_f32_e32 v6, v6
	v_cvt_i32_f32_e32 v7, v7
	v_mul_f32_e32 v37, v12, v58
	v_mul_f32_e32 v38, v12, v59
	v_rndne_f32_e32 v37, v37
	v_rndne_f32_e32 v38, v38
	v_cvt_i32_f32_e32 v37, v37
	v_cvt_i32_f32_e32 v38, v38
	v_add_u32_e32 v27, 8, v6
	v_add_u32_e32 v36, 8, v7
	v_lshrrev_b32_e32 v27, 4, v27
	v_and_b32_e32 v36, 0xf0, v36
	v_and_or_b32 v27, v27, 15, v36
	v_lshl_add_u32 v36, v37, 4, v122
	v_lshl_add_u32 v39, v38, 8, v123
	v_and_b32_e32 v36, 0xf00, v36
	v_and_b32_e32 v39, 0xf000, v39
	v_mul_f32_e32 v42, v12, v60
	v_or3_b32 v27, v27, v36, v39
	v_mul_f32_e32 v39, v12, v40
	v_rndne_f32_e32 v42, v42
	v_rndne_f32_e32 v39, v39
	v_cvt_i32_f32_e32 v42, v42
	v_cvt_i32_f32_e32 v39, v39
	v_mul_f32_e32 v43, v12, v61
	v_mul_f32_e32 v12, v12, v41
	v_rndne_f32_e32 v12, v12
	v_rndne_f32_e32 v43, v43
	v_cvt_i32_f32_e32 v12, v12
	v_lshlrev_b32_e32 v36, 12, v38
	v_cvt_i32_f32_e32 v43, v43
	v_and_b32_e32 v38, 0xf000, v36
	v_lshl_add_u32 v36, v42, 12, v124
	v_lshlrev_b32_e32 v40, 16, v42
	v_lshl_add_u32 v42, v39, 16, v125
	v_and_b32_e32 v6, 15, v6
	v_lshlrev_b32_e32 v7, 4, v7
	v_lshlrev_b32_e32 v37, 8, v37
	v_and_b32_e32 v36, 0xf0000, v36
	v_and_b32_e32 v42, 0xf00000, v42
	v_and_b32_e32 v7, 0xf0, v7
	v_and_b32_e32 v37, 0xf00, v37
	v_or3_b32 v27, v27, v36, v42
	v_lshlrev_b32_e32 v36, 20, v39
	v_lshl_or_b32 v6, v12, 28, v6
	v_and_b32_e32 v40, 0xf0000, v40
	v_and_b32_e32 v39, 0xf00000, v36
	v_lshl_add_u32 v36, v43, 20, v126
	v_lshlrev_b32_e32 v41, 24, v43
	v_lshl_add_u32 v42, v12, 24, v127
	v_or3_b32 v6, v6, v7, v37
	v_and_b32_e32 v36, 0xf000000, v36
	v_and_b32_e32 v41, 0xf000000, v41
	v_and_b32_e32 v42, 0xf0000000, v42
	v_or3_b32 v6, v6, v38, v40
	v_or3_b32 v36, v27, v36, v42
	v_or3_b32 v37, v6, v39, v41
	ds_write_b128 v128, v[34:37] offset:3584
	s_waitcnt vmcnt(3)
	v_cmp_gt_u32_e32 vcc, s37, v2
	s_waitcnt vmcnt(2)
; __device__ __forceinline__ void p3_token(const Params& p, int tok, int lane, unsigned* rec, float& sh, int& hs8) {
;     ...
;     const int k0 = e0 >> 11, k1 = e1 >> 11;
;     int pos0 = 0, pos1 = 0, base = 0;
; #pragma unroll
;     for (int v = 0; v < 8; v++) {
;         const unsigned long long m0 = __ballot(k0 == v), m1 = __ballot(k1 == v);
;         const int c0 = __popcll(m0);
;         const int r0 = __builtin_amdgcn_mbcnt_hi((unsigned)(m0 >> 32), __builtin_amdgcn_mbcnt_lo((unsigned)m0, 0u));
;         const int r1 = __builtin_amdgcn_mbcnt_hi((unsigned)(m1 >> 32), __builtin_amdgcn_mbcnt_lo((unsigned)m1, 0u));
;         pos0 = (k0 == v) ? base + r0 : pos0;
;         pos1 = (k1 == v) ? base + c0 + r1 : pos1;
;         base += c0 + __popcll(m1);
;     }
;     const float* tsc = (const float*)(p.ws + OFF_UB + 33554432);
;     const f32x2 s0 = *(const f32x2*)(tsc + 2 * e0), s1 = *(const f32x2*)(tsc + 2 * e1);
;     rec[pos0] = (unsigned)e0; rec[pos1] = (unsigned)e1;
;     rec[128 + pos0] = __float_as_uint(g0 * s0[1]); rec[128 + pos1] = __float_as_uint(g1 * s1[1]);
;     rec[512 + pos0] = __float_as_uint(sh * s0[0]); rec[512 + pos1] = __float_as_uint(sh * s1[0]);
; __device__ void phaseP3(const Params& p, float* dstp, char* lds) {
;     ...
; #pragma unroll
;         for (int k = 0; k < TPW; k++) {
;             p3_load_u(ur[k], sc[k], UQ, tsc, lane, ul, 0, recs + k * (P3_REC / 4));
;             p3_load_v(vr[k], VQ, lane, 0, recs + k * (P3_REC / 4));
;         }
	v_cmp_gt_u32_e64 s[4:5], s37, v3
	s_bcnt1_i32_b64 s8, vcc
	s_and_saveexec_b64 s[6:7], s[4:5]
	v_mbcnt_lo_u32_b32 v0, s4, 0
	v_mbcnt_hi_u32_b32 v0, s5, v0
	v_add_u32_e32 v0, s8, v0
	s_or_b64 exec, exec, s[6:7]
	v_ashrrev_i32_e32 v6, 11, v2
	s_bcnt1_i32_b64 s42, s[4:5]
	v_cmp_eq_u32_e64 s[4:5], 1, v6
	v_ashrrev_i32_e32 v7, 11, v3
	s_add_i32 s42, s42, s8
	s_bcnt1_i32_b64 s8, s[4:5]
	v_cmp_eq_u32_e64 s[6:7], 1, v7
	s_add_i32 s43, s42, s8
	s_and_saveexec_b64 s[8:9], s[6:7]
	v_mbcnt_lo_u32_b32 v0, s6, 0
	v_mbcnt_hi_u32_b32 v0, s7, v0
	v_add_u32_e32 v0, s43, v0
	s_or_b64 exec, exec, s[8:9]
	s_bcnt1_i32_b64 s6, s[6:7]
	s_add_i32 s43, s43, s6
	v_cmp_eq_u32_e64 s[6:7], 2, v6
	s_bcnt1_i32_b64 s10, s[6:7]
	v_cmp_eq_u32_e64 s[8:9], 2, v7
	s_add_i32 s44, s43, s10
	s_and_saveexec_b64 s[10:11], s[8:9]
	v_mbcnt_lo_u32_b32 v0, s8, 0
	v_mbcnt_hi_u32_b32 v0, s9, v0
	v_add_u32_e32 v0, s44, v0
	s_or_b64 exec, exec, s[10:11]
	s_bcnt1_i32_b64 s8, s[8:9]
	s_add_i32 s44, s44, s8
	v_cmp_eq_u32_e64 s[8:9], 3, v6
	s_bcnt1_i32_b64 s12, s[8:9]
	v_cmp_eq_u32_e64 s[10:11], 3, v7
	s_add_i32 s45, s44, s12
	s_and_saveexec_b64 s[12:13], s[10:11]
	v_mbcnt_lo_u32_b32 v0, s10, 0
	v_mbcnt_hi_u32_b32 v0, s11, v0
	v_add_u32_e32 v0, s45, v0
	s_or_b64 exec, exec, s[12:13]
	s_bcnt1_i32_b64 s10, s[10:11]
	s_add_i32 s45, s45, s10
	v_cmp_eq_u32_e64 s[10:11], 4, v6
	s_bcnt1_i32_b64 s14, s[10:11]
	v_cmp_eq_u32_e64 s[12:13], 4, v7
	s_add_i32 s46, s45, s14
	s_and_saveexec_b64 s[14:15], s[12:13]
	v_mbcnt_lo_u32_b32 v0, s12, 0
	v_mbcnt_hi_u32_b32 v0, s13, v0
	v_add_u32_e32 v0, s46, v0
	s_or_b64 exec, exec, s[14:15]
	s_bcnt1_i32_b64 s12, s[12:13]
	s_add_i32 s46, s46, s12
	v_cmp_eq_u32_e64 s[12:13], 5, v6
	s_bcnt1_i32_b64 s16, s[12:13]
	v_cmp_eq_u32_e64 s[14:15], 5, v7
	s_add_i32 s47, s46, s16
	s_and_saveexec_b64 s[16:17], s[14:15]
	v_mbcnt_lo_u32_b32 v0, s14, 0
	v_mbcnt_hi_u32_b32 v0, s15, v0
	v_add_u32_e32 v0, s47, v0
	s_or_b64 exec, exec, s[16:17]
	s_bcnt1_i32_b64 s14, s[14:15]
	s_add_i32 s47, s47, s14
	v_cmp_eq_u32_e64 s[14:15], 6, v6
	s_bcnt1_i32_b64 s18, s[14:15]
	v_cmp_eq_u32_e64 s[16:17], 6, v7
	s_add_i32 s48, s47, s18
	s_and_saveexec_b64 s[18:19], s[16:17]
	v_mbcnt_lo_u32_b32 v0, s16, 0
	v_mbcnt_hi_u32_b32 v0, s17, v0
	v_add_u32_e32 v0, s48, v0
	s_or_b64 exec, exec, s[18:19]
	s_bcnt1_i32_b64 s16, s[16:17]
	s_add_i32 s48, s48, s16
	v_cmp_eq_u32_e64 s[16:17], 7, v6
	v_cmp_eq_u32_e64 s[18:19], 7, v7
	s_and_saveexec_b64 s[34:35], s[18:19]
	s_bcnt1_i32_b64 s49, s[16:17]
	v_mbcnt_lo_u32_b32 v0, s18, 0
	s_add_i32 s49, s48, s49
	v_mbcnt_hi_u32_b32 v0, s19, v0
	v_add_u32_e32 v0, s49, v0
	s_or_b64 exec, exec, s[34:35]
	v_lshlrev_b32_e32 v6, 1, v2
	v_ashrrev_i32_e32 v7, 31, v6
	v_lshlrev_b32_e32 v34, 1, v3
	v_lshl_add_u64 v[6:7], v[6:7], 2, s[26:27]
	v_ashrrev_i32_e32 v35, 31, v34
	v_lshl_add_u64 v[34:35], v[34:35], 2, s[26:27]
	global_load_dwordx2 v[36:37], v[6:7], off
	global_load_dwordx2 v[38:39], v[34:35], off
	v_mbcnt_lo_u32_b32 v41, s4, 0
	v_mbcnt_lo_u32_b32 v42, vcc_lo, 0
	v_mbcnt_lo_u32_b32 v40, s6, 0
	v_mbcnt_hi_u32_b32 v41, s5, v41
	v_mbcnt_hi_u32_b32 v42, vcc_hi, v42
	v_mbcnt_lo_u32_b32 v34, s8, 0
	v_mbcnt_hi_u32_b32 v40, s7, v40
	v_add_u32_e32 v41, s42, v41
	v_cndmask_b32_e32 v42, 0, v42, vcc
	v_mbcnt_lo_u32_b32 v27, s10, 0
	v_mbcnt_hi_u32_b32 v34, s9, v34
	v_add_u32_e32 v40, s43, v40
	v_cndmask_b32_e64 v41, v42, v41, s[4:5]
	v_mbcnt_lo_u32_b32 v12, s12, 0
	v_mbcnt_hi_u32_b32 v27, s11, v27
	v_add_u32_e32 v34, s44, v34
	v_cndmask_b32_e64 v40, v41, v40, s[6:7]
	v_mbcnt_lo_u32_b32 v7, s14, 0
	v_mbcnt_hi_u32_b32 v12, s13, v12
	v_add_u32_e32 v27, s45, v27
	v_cndmask_b32_e64 v34, v40, v34, s[8:9]
	v_mbcnt_lo_u32_b32 v6, s16, 0
	v_mbcnt_hi_u32_b32 v7, s15, v7
	v_add_u32_e32 v12, s46, v12
	v_cndmask_b32_e64 v27, v34, v27, s[10:11]
	v_mbcnt_hi_u32_b32 v6, s17, v6
	v_add_u32_e32 v7, s47, v7
	v_cndmask_b32_e64 v12, v27, v12, s[12:13]
	v_add_u32_e32 v6, s48, v6
	v_cndmask_b32_e64 v7, v12, v7, s[14:15]
	v_cndmask_b32_e64 v6, v7, v6, s[16:17]
	v_mul_f32_e32 v1, 0x3c09ae41, v1
	v_lshl_add_u32 v6, v6, 2, v11
	v_lshl_add_u32 v0, v0, 2, v11
	ds_write_b32 v6, v2 offset:2560
	ds_write_b32 v0, v3 offset:2560
	v_mov_b32_e32 v35, v13
	v_mov_b32_e32 v41, v13
	s_mov_b32 s5, 0
	s_waitcnt vmcnt(1)
	v_mul_f32_e32 v2, v4, v37
	s_waitcnt vmcnt(0)
	v_mul_f32_e32 v3, v5, v39
	v_mul_f32_e32 v4, v1, v36
	v_mul_f32_e32 v1, v1, v38
	ds_write_b32 v6, v2 offset:3072
	ds_write_b32 v0, v3 offset:3072
	ds_write_b32 v6, v4 offset:4608
	ds_write_b32 v0, v1 offset:4608
	ds_read_b128 v[0:3], v11
	ds_read_b128 v[4:7], v11 offset:2560
	v_mov_b32_e32 v37, v13
	v_mov_b32_e32 v39, v13
	s_waitcnt lgkmcnt(1)
	v_mov_b32_e32 v12, v0
	v_mov_b32_e32 v34, v1
	v_mov_b32_e32 v36, v3
	s_waitcnt lgkmcnt(0)
; __device__ __forceinline__ void p3_dots(const u32x2 (&ur)[4], const unsigned* rec, int lane, int (&pt)[4]) {
;     const u32x4 qh = *(const u32x4*)(rec + 256 + lane * 4);
; #pragma unroll
;     for (int u = 0; u < 4; u++) {
;         const int w0 = (int)ur[u].x, w1 = (int)ur[u].y;
;         int dh = __builtin_amdgcn_sdot8(w0, (int)qh.x, 0, false);
;         dh = __builtin_amdgcn_sdot8(w1, (int)qh.z, dh, false);
;         int dl = __builtin_amdgcn_sdot8(w0, (int)qh.y, 0, false);
;         dl = __builtin_amdgcn_sdot8(w1, (int)qh.w, dl, false);
;         pt[u] = (dh << 4) + dl;
;     }
; }
; template <int CTRL> __device__ __forceinline__ int dpp_i(int v) { return __builtin_amdgcn_mov_dpp(v, CTRL, 0xF, 0xF, true); }
; __device__ __forceinline__ int xrow_sum_i(int v) {
;     const auto a = __builtin_amdgcn_permlane16_swap((unsigned)v, (unsigned)v, false, false);
;     v = (int)a[0] + (int)a[1];
; __device__ void phaseP3(const Params& p, float* dstp, char* lds) {
;     ...
; #pragma unroll
;         for (int k = 0; k < TPW; k++) {
;             p3_load_u(ur[k], sc[k], UQ, tsc, lane, ul, 0, recs + k * (P3_REC / 4));
;             p3_load_v(vr[k], VQ, lane, 0, recs + k * (P3_REC / 4));
;         }
;         for (int g = 0; g < 32; g++) {
; #pragma unroll
;             for (int k = 0; k < TPW; k++) {
;                 int pt[4];
;                 p3_dots(ur[k], recs + k * (P3_REC / 4), lane, pt);
;                 const P3Sc sck = sc[k];
;                 if (g + 1 < 32) p3_load_u(ur[k], sc[k], UQ, tsc, lane, ul, g + 1, recs + k * (P3_REC / 4));
;                 const float w = p3_weight(pt, lane, sh[k], hs8[k], sck);
;                 p3_axpy(vr[k], w, acc[k]);
;                 if (g + 1 < 32) p3_load_v(vr[k], VQ, lane, g + 1, recs + k * (P3_REC / 4));
	v_mov_b32_e32 v38, v5
	v_mov_b32_e32 v40, v7
	v_lshlrev_b64 v[0:1], 9, v[34:35]
	v_lshlrev_b64 v[34:35], 9, v[12:13]
	v_mov_b32_e32 v12, v2
	v_lshlrev_b64 v[2:3], 9, v[36:37]
	v_lshlrev_b64 v[36:37], 9, v[38:39]
	v_lshlrev_b64 v[38:39], 9, v[40:41]
	v_lshl_add_u64 v[40:41], v[14:15], 0, v[34:35]
	v_lshlrev_b64 v[44:45], 9, v[12:13]
	v_lshl_add_u64 v[42:43], v[14:15], 0, v[0:1]
	v_lshl_add_u64 v[46:47], v[14:15], 0, v[2:3]
	v_lshl_add_u64 v[34:35], v[16:17], 0, v[34:35]
	v_lshl_add_u64 v[0:1], v[16:17], 0, v[0:1]
	v_lshl_add_u64 v[2:3], v[16:17], 0, v[2:3]
	v_mov_b32_e32 v12, v4
	v_lshl_add_u64 v[50:51], v[14:15], 0, v[44:45]
	v_lshl_add_u64 v[44:45], v[16:17], 0, v[44:45]
	global_load_dwordx2 v[80:81], v[40:41], off
	global_load_dwordx2 v[74:75], v[42:43], off
	global_load_dwordx2 v[84:85], v[50:51], off
	global_load_dwordx2 v[82:83], v[46:47], off
	global_load_dwordx2 v[72:73], v[34:35], off
	global_load_dwordx2 v[70:71], v[0:1], off
	global_load_dwordx2 v[62:63], v[44:45], off
	global_load_dwordx2 v[58:59], v[2:3], off
	v_lshlrev_b64 v[52:53], 9, v[12:13]
	v_mov_b32_e32 v12, v6
	v_lshl_add_u64 v[0:1], v[14:15], 0, v[52:53]
	v_lshlrev_b64 v[2:3], 9, v[12:13]
	v_lshl_add_u64 v[4:5], v[14:15], 0, v[36:37]
	v_lshl_add_u64 v[48:49], v[14:15], 0, v[38:39]
	v_lshl_add_u64 v[6:7], v[14:15], 0, v[2:3]
	global_load_dwordx2 v[66:67], v[0:1], off
	global_load_dwordx2 v[60:61], v[4:5], off
	global_load_dwordx2 v[68:69], v[6:7], off
	global_load_dwordx2 v[64:65], v[48:49], off
	v_lshl_add_u64 v[0:1], v[16:17], 0, v[52:53]
	v_lshl_add_u64 v[4:5], v[16:17], 0, v[36:37]
	v_lshl_add_u64 v[2:3], v[16:17], 0, v[2:3]
	v_lshl_add_u64 v[6:7], v[16:17], 0, v[38:39]
	global_load_dwordx2 v[40:41], v[0:1], off
	global_load_dwordx2 v[38:39], v[4:5], off
	global_load_dwordx2 v[36:37], v[2:3], off
	global_load_dwordx2 v[34:35], v[6:7], off
	ds_read2st64_b32 v[76:77], v119 offset0:2 offset1:8
	ds_read2st64_b32 v[78:79], v119 offset0:12 offset1:18
	ds_read_b128 v[4:7], v128 offset:1024
	ds_read_b128 v[0:3], v128 offset:3584
	v_mov_b32_e32 v42, 0
	v_mov_b32_e32 v43, v42
	v_mov_b32_e32 v44, v42
	v_mov_b32_e32 v45, v42
	v_mov_b32_e32 v46, v42
	v_mov_b32_e32 v47, v42
	v_mov_b32_e32 v48, v42
	v_mov_b32_e32 v49, v42
	v_mov_b32_e32 v50, v42
	v_mov_b32_e32 v51, v42
	v_mov_b32_e32 v52, v42
	v_mov_b32_e32 v53, v42
	v_mov_b32_e32 v86, v42
	v_mov_b32_e32 v87, v42
	v_mov_b32_e32 v88, v42
	v_mov_b32_e32 v89, v42
	v_mov_b32_e32 v90, v42
	v_mov_b32_e32 v91, v42
	v_mov_b32_e32 v92, v42
	v_mov_b32_e32 v93, v42
	v_mov_b32_e32 v94, v42
	v_mov_b32_e32 v95, v42
	v_mov_b32_e32 v96, v42
	v_mov_b32_e32 v97, v42
	v_mov_b32_e32 v98, v42
	v_mov_b32_e32 v99, v42
	v_mov_b32_e32 v100, v42
	v_mov_b32_e32 v101, v42
	v_mov_b32_e32 v54, v42
	v_mov_b32_e32 v55, v42
	v_mov_b32_e32 v56, v42
	v_mov_b32_e32 v57, v42
	s_waitcnt lgkmcnt(0)
	v_cndmask_b32_e64 v76, v76, v78, s[54:55]
	v_cndmask_b32_e64 v77, v77, v79, s[54:55]
.LBB0_1075:
	v_add_u32_e32 v134, s5, v121
	v_add_u32_e32 v135, s5, v137
	ds_read_b128 v[140:143], v134
	ds_read_b128 v[144:147], v134 offset:2560
	s_waitcnt vmcnt(12) lgkmcnt(2)
	v_dot8_i32_i4 v12, v80, v4, 0
	v_dot8_i32_i4 v27, v80, v5, 0
	v_dot8_i32_i4 v131, v74, v4, 0
	v_dot8_i32_i4 v132, v74, v5, 0
	v_dot8c_i32_i4_e32 v12, v81, v6
	v_dot8c_i32_i4_e32 v27, v81, v7
	v_dot8c_i32_i4_e32 v131, v75, v6
	v_dot8c_i32_i4_e32 v132, v75, v7
	v_dot8_i32_i4 v133, v84, v4, 0
	v_dot8_i32_i4 v176, v84, v5, 0
	v_dot8_i32_i4 v177, v82, v4, 0
	v_dot8_i32_i4 v178, v82, v5, 0
	v_dot8c_i32_i4_e32 v133, v85, v6
	v_dot8c_i32_i4_e32 v176, v85, v7
	v_dot8c_i32_i4_e32 v177, v83, v6
	v_dot8c_i32_i4_e32 v178, v83, v7
	v_lshl_add_u32 v27, v12, 4, v27
	v_lshl_add_u32 v131, v131, 4, v132
	v_lshl_add_u32 v132, v133, 4, v176
	v_lshl_add_u32 v133, v177, 4, v178
	v_cndmask_b32_e64 v12, v132, v27, s[0:1]
	v_cndmask_b32_e64 v27, v27, v132, s[0:1]
	s_waitcnt lgkmcnt(0)
	v_lshl_add_u32 v140, v140, 9, v136
	v_add_u32_dpp v12, v27, v12 quad_perm:[1,0,3,2] row_mask:0xf bank_mask:0xf bound_ctrl:1
	v_cndmask_b32_e64 v27, v133, v131, s[0:1]
	v_cndmask_b32_e64 v131, v131, v133, s[0:1]
	v_lshl_add_u32 v141, v141, 9, v136
	v_lshl_add_u32 v142, v142, 9, v136
	v_add_u32_dpp v27, v131, v27 quad_perm:[1,0,3,2] row_mask:0xf bank_mask:0xf bound_ctrl:1
	v_cndmask_b32_e64 v131, v27, v12, s[2:3]
	v_cndmask_b32_e64 v12, v12, v27, s[2:3]
	v_lshl_add_u32 v143, v143, 9, v136
	global_load_dwordx2 v[80:81], v140, s[50:51]
	v_add_u32_dpp v12, v12, v131 quad_perm:[2,3,0,1] row_mask:0xf bank_mask:0xf bound_ctrl:1
	global_load_dwordx2 v[74:75], v141, s[50:51]
	global_load_dwordx2 v[84:85], v142, s[50:51]
	v_add_u32_dpp v12, v12, v12 row_ror:4 row_mask:0xf bank_mask:0xf bound_ctrl:1
	global_load_dwordx2 v[82:83], v143, s[50:51]
	s_waitcnt vmcnt(8)
; __device__ __forceinline__ void p3_dots(const u32x2 (&ur)[4], const unsigned* rec, int lane, int (&pt)[4]) {
;     const u32x4 qh = *(const u32x4*)(rec + 256 + lane * 4);
; #pragma unroll
;     for (int u = 0; u < 4; u++) {
;         const int w0 = (int)ur[u].x, w1 = (int)ur[u].y;
;         int dh = __builtin_amdgcn_sdot8(w0, (int)qh.x, 0, false);
;         dh = __builtin_amdgcn_sdot8(w1, (int)qh.z, dh, false);
;         int dl = __builtin_amdgcn_sdot8(w0, (int)qh.y, 0, false);
;         dl = __builtin_amdgcn_sdot8(w1, (int)qh.w, dl, false);
;         pt[u] = (dh << 4) + dl;
;     }
; }
; template <int CTRL> __device__ __forceinline__ int dpp_i(int v) { return __builtin_amdgcn_mov_dpp(v, CTRL, 0xF, 0xF, true); }
; __device__ __forceinline__ int xrow_sum_i(int v) {
;     const auto a = __builtin_amdgcn_permlane16_swap((unsigned)v, (unsigned)v, false, false);
;     v = (int)a[0] + (int)a[1];
;     const auto b = __builtin_amdgcn_permlane32_swap((unsigned)v, (unsigned)v, false, false);
;     return (int)b[0] + (int)b[1];
; }
; __device__ __forceinline__ float p3_weight(const int (&pt)[4], int lane, float sh, int hs8, const P3Sc& sc) {
;     int m2[2], m1;
;     const bool c0 = lane & 1;
; #pragma unroll
;     for (int j = 0; j < 2; j++) { const int keep = c0 ? pt[j + 2] : pt[j], send = c0 ? pt[j] : pt[j + 2]; m2[j] = keep + dpp_i<0xB1>(send); }
;     const bool c1 = lane & 2;
;     { const int keep = c1 ? m2[1] : m2[0], send = c1 ? m2[0] : m2[1]; m1 = keep + dpp_i<0x4E>(send); }
;     m1 += dpp_i<0x124>(m1);
;     m1 += dpp_i<0x128>(m1);
;     m1 = xrow_sum_i(m1);
;     const float aval = (float)(m1 - hs8) * sc.su;
;     return sc.gm * gelu_erf(aval);
; }
	v_add_u32_dpp v181, v12, v12 row_ror:8 row_mask:0xf bank_mask:0xf bound_ctrl:1
	v_dot8_i32_i4 v12, v66, v0, 0
	v_dot8_i32_i4 v27, v66, v1, 0
	v_dot8_i32_i4 v131, v60, v0, 0
	v_dot8_i32_i4 v132, v60, v1, 0
	v_dot8c_i32_i4_e32 v12, v67, v2
	v_dot8c_i32_i4_e32 v27, v67, v3
	v_dot8c_i32_i4_e32 v131, v61, v2
	v_dot8c_i32_i4_e32 v132, v61, v3
	v_dot8_i32_i4 v133, v68, v0, 0
	v_dot8_i32_i4 v176, v68, v1, 0
	v_dot8_i32_i4 v177, v64, v0, 0
	v_dot8_i32_i4 v178, v64, v1, 0
	v_dot8c_i32_i4_e32 v133, v69, v2
	v_dot8c_i32_i4_e32 v176, v69, v3
	v_dot8c_i32_i4_e32 v177, v65, v2
	v_dot8c_i32_i4_e32 v178, v65, v3
	v_lshl_add_u32 v27, v12, 4, v27
	v_lshl_add_u32 v131, v131, 4, v132
	v_lshl_add_u32 v132, v133, 4, v176
	v_lshl_add_u32 v133, v177, 4, v178
	v_cndmask_b32_e64 v12, v132, v27, s[0:1]
	v_cndmask_b32_e64 v27, v27, v132, s[0:1]
	v_lshl_add_u32 v144, v144, 9, v136
	v_lshl_add_u32 v145, v145, 9, v136
	v_add_u32_dpp v12, v27, v12 quad_perm:[1,0,3,2] row_mask:0xf bank_mask:0xf bound_ctrl:1
	v_cndmask_b32_e64 v27, v133, v131, s[0:1]
	v_cndmask_b32_e64 v131, v131, v133, s[0:1]
	v_lshl_add_u32 v146, v146, 9, v136
	v_lshl_add_u32 v147, v147, 9, v136
	v_add_u32_dpp v27, v131, v27 quad_perm:[1,0,3,2] row_mask:0xf bank_mask:0xf bound_ctrl:1
	v_cndmask_b32_e64 v131, v27, v12, s[2:3]
	v_cndmask_b32_e64 v12, v12, v27, s[2:3]
	global_load_dwordx2 v[66:67], v144, s[50:51]
	global_load_dwordx2 v[60:61], v145, s[50:51]
	v_add_u32_dpp v12, v12, v131 quad_perm:[2,3,0,1] row_mask:0xf bank_mask:0xf bound_ctrl:1
	global_load_dwordx2 v[68:69], v146, s[50:51]
	global_load_dwordx2 v[64:65], v147, s[50:51]
	v_add_u32_dpp v12, v12, v12 row_ror:4 row_mask:0xf bank_mask:0xf bound_ctrl:1
	v_cvt_scalef32_pk_f32_fp4 v[160:161], v72, 1.0
	v_cvt_scalef32_pk_f32_fp4 v[162:163], v72, 1.0 op_sel:[1,0,0]
	v_add_u32_dpp v12, v12, v12 row_ror:8 row_mask:0xf bank_mask:0xf bound_ctrl:1
	v_cvt_scalef32_pk_f32_fp4 v[164:165], v72, 1.0 op_sel:[0,1,0]
	v_cvt_scalef32_pk_f32_fp4 v[166:167], v72, 1.0 op_sel:[1,1,0]
	v_permlane16_swap_b32_e32 v181, v12
	v_add_u32_e32 v12, v181, v12
	v_mov_b32_e32 v27, v12
	v_cvt_scalef32_pk_f32_fp4 v[168:169], v73, 1.0
	v_cvt_scalef32_pk_f32_fp4 v[170:171], v73, 1.0 op_sel:[1,0,0]
	v_permlane32_swap_b32_e32 v12, v27
	v_add_u32_e32 v12, v27, v12
	v_cvt_f32_i32_e32 v12, v12
	v_mul_f32_e32 v12, v77, v12
	v_fma_f32 v179, |v12|, s39, 1.0
	v_rcp_f32_e32 v179, v179
	v_cmp_gt_f32_e32 vcc, 0, v12
	v_fmamk_f32 v180, v179, 0x3f07dc22, v129
	v_fmaak_f32 v180, v179, v180, 0x3f35f0e3
	v_fmaak_f32 v180, v179, v180, 0xbe11a98e
	v_fmaak_f32 v180, v179, v180, 0x3e027906
	v_mul_f32_e32 v179, v179, v180
	v_mul_f32_e32 v180, v12, v12
	v_mul_f32_e32 v180, 0xbf38aa3b, v180
	v_exp_f32_e32 v180, v180
	v_cvt_scalef32_pk_f32_fp4 v[172:173], v73, 1.0 op_sel:[0,1,0]
	v_mul_f32_e32 v179, v180, v179
	v_mul_f32_e32 v180, v12, v179
	v_fma_f32 v12, -v12, v179, v12
	v_cndmask_b32_e32 v12, v12, v180, vcc
	v_mul_f32_e32 v12, v76, v12
	ds_read2st64_b32 v[76:77], v135 offset1:6
	v_readlane_b32 s4, v12, 0
	v_cvt_scalef32_pk_f32_fp4 v[174:175], v73, 1.0 op_sel:[1,1,0]
	global_load_dwordx2 v[72:73], v140, s[52:53]
	v_pk_fma_f32 v[100:101], s[4:5], v[160:161], v[100:101] op_sel_hi:[0,1,1]
	v_pk_fma_f32 v[98:99], s[4:5], v[162:163], v[98:99] op_sel_hi:[0,1,1]
	v_pk_fma_f32 v[96:97], s[4:5], v[164:165], v[96:97] op_sel_hi:[0,1,1]
	v_pk_fma_f32 v[94:95], s[4:5], v[166:167], v[94:95] op_sel_hi:[0,1,1]
	v_pk_fma_f32 v[92:93], s[4:5], v[168:169], v[92:93] op_sel_hi:[0,1,1]
	v_pk_fma_f32 v[90:91], s[4:5], v[170:171], v[90:91] op_sel_hi:[0,1,1]
	v_pk_fma_f32 v[88:89], s[4:5], v[172:173], v[88:89] op_sel_hi:[0,1,1]
	v_pk_fma_f32 v[86:87], s[4:5], v[174:175], v[86:87] op_sel_hi:[0,1,1]
	v_readlane_b32 s4, v12, 2
	v_cvt_scalef32_pk_f32_fp4 v[160:161], v70, 1.0
	v_cvt_scalef32_pk_f32_fp4 v[162:163], v70, 1.0 op_sel:[1,0,0]
	v_pk_fma_f32 v[100:101], s[4:5], v[160:161], v[100:101] op_sel_hi:[0,1,1]
	v_cvt_scalef32_pk_f32_fp4 v[164:165], v70, 1.0 op_sel:[0,1,0]
	v_pk_fma_f32 v[98:99], s[4:5], v[162:163], v[98:99] op_sel_hi:[0,1,1]
	v_cvt_scalef32_pk_f32_fp4 v[166:167], v70, 1.0 op_sel:[1,1,0]
	v_pk_fma_f32 v[96:97], s[4:5], v[164:165], v[96:97] op_sel_hi:[0,1,1]
	v_cvt_scalef32_pk_f32_fp4 v[168:169], v71, 1.0
	v_pk_fma_f32 v[94:95], s[4:5], v[166:167], v[94:95] op_sel_hi:[0,1,1]
	v_cvt_scalef32_pk_f32_fp4 v[170:171], v71, 1.0 op_sel:[1,0,0]
	v_pk_fma_f32 v[92:93], s[4:5], v[168:169], v[92:93] op_sel_hi:[0,1,1]
	v_cvt_scalef32_pk_f32_fp4 v[172:173], v71, 1.0 op_sel:[0,1,0]
	v_pk_fma_f32 v[90:91], s[4:5], v[170:171], v[90:91] op_sel_hi:[0,1,1]
	v_cvt_scalef32_pk_f32_fp4 v[174:175], v71, 1.0 op_sel:[1,1,0]
	v_pk_fma_f32 v[88:89], s[4:5], v[172:173], v[88:89] op_sel_hi:[0,1,1]
	v_pk_fma_f32 v[86:87], s[4:5], v[174:175], v[86:87] op_sel_hi:[0,1,1]
	global_load_dwordx2 v[70:71], v141, s[52:53]
	v_readlane_b32 s4, v12, 1
	v_cvt_scalef32_pk_f32_fp4 v[160:161], v62, 1.0
	v_cvt_scalef32_pk_f32_fp4 v[162:163], v62, 1.0 op_sel:[1,0,0]
	v_pk_fma_f32 v[100:101], s[4:5], v[160:161], v[100:101] op_sel_hi:[0,1,1]
	v_cvt_scalef32_pk_f32_fp4 v[164:165], v62, 1.0 op_sel:[0,1,0]
	v_pk_fma_f32 v[98:99], s[4:5], v[162:163], v[98:99] op_sel_hi:[0,1,1]
	v_cvt_scalef32_pk_f32_fp4 v[166:167], v62, 1.0 op_sel:[1,1,0]
	v_pk_fma_f32 v[96:97], s[4:5], v[164:165], v[96:97] op_sel_hi:[0,1,1]
	v_cvt_scalef32_pk_f32_fp4 v[168:169], v63, 1.0
	v_pk_fma_f32 v[94:95], s[4:5], v[166:167], v[94:95] op_sel_hi:[0,1,1]
	v_cvt_scalef32_pk_f32_fp4 v[170:171], v63, 1.0 op_sel:[1,0,0]
	v_pk_fma_f32 v[92:93], s[4:5], v[168:169], v[92:93] op_sel_hi:[0,1,1]
	v_cvt_scalef32_pk_f32_fp4 v[172:173], v63, 1.0 op_sel:[0,1,0]
	v_pk_fma_f32 v[90:91], s[4:5], v[170:171], v[90:91] op_sel_hi:[0,1,1]
; __device__ __forceinline__ void p3_axpy(const u32x2 (&vr)[4], float ws, f32x2 (&acc)[8]) {
; #pragma unroll
;     for (int u = 0; u < 4; u++) {
;         const int la = ((u >> 1) & 1) | ((u & 1) << 1);
;         const float wu = __builtin_bit_cast(float, __builtin_amdgcn_readlane(__builtin_bit_cast(int, ws), la));
;         const f32x2 w2 = {wu, wu};
;         const unsigned vw[2] = {vr[u].x, vr[u].y};
; #pragma unroll
;         for (int i = 0; i < 2; i++) {
;             acc[i * 4 + 0] = __builtin_elementwise_fma(w2, __builtin_amdgcn_cvt_scalef32_pk_f32_fp4(vw[i], 1.0f, 0), acc[i * 4 + 0]);
;             acc[i * 4 + 1] = __builtin_elementwise_fma(w2, __builtin_amdgcn_cvt_scalef32_pk_f32_fp4(vw[i], 1.0f, 1), acc[i * 4 + 1]);
;             acc[i * 4 + 2] = __builtin_elementwise_fma(w2, __builtin_amdgcn_cvt_scalef32_pk_f32_fp4(vw[i], 1.0f, 2), acc[i * 4 + 2]);
;             acc[i * 4 + 3] = __builtin_elementwise_fma(w2, __builtin_amdgcn_cvt_scalef32_pk_f32_fp4(vw[i], 1.0f, 3), acc[i * 4 + 3]);
;         }
;     }
; }
; __device__ void phaseP3(const Params& p, float* dstp, char* lds) {
;     ...
;         for (int g = 0; g < 32; g++) {
; #pragma unroll
;             for (int k = 0; k < TPW; k++) {
;                 int pt[4];
;                 p3_dots(ur[k], recs + k * (P3_REC / 4), lane, pt);
;                 const P3Sc sck = sc[k];
;                 if (g + 1 < 32) p3_load_u(ur[k], sc[k], UQ, tsc, lane, ul, g + 1, recs + k * (P3_REC / 4));
;                 const float w = p3_weight(pt, lane, sh[k], hs8[k], sck);
;                 p3_axpy(vr[k], w, acc[k]);
;                 if (g + 1 < 32) p3_load_v(vr[k], VQ, lane, g + 1, recs + k * (P3_REC / 4));
;             }
;         }
	v_cvt_scalef32_pk_f32_fp4 v[174:175], v63, 1.0 op_sel:[1,1,0]
	v_pk_fma_f32 v[88:89], s[4:5], v[172:173], v[88:89] op_sel_hi:[0,1,1]
	v_pk_fma_f32 v[86:87], s[4:5], v[174:175], v[86:87] op_sel_hi:[0,1,1]
	global_load_dwordx2 v[62:63], v142, s[52:53]
	v_readlane_b32 s4, v12, 3
	v_cvt_scalef32_pk_f32_fp4 v[160:161], v58, 1.0
	v_cvt_scalef32_pk_f32_fp4 v[162:163], v58, 1.0 op_sel:[1,0,0]
	v_pk_fma_f32 v[100:101], s[4:5], v[160:161], v[100:101] op_sel_hi:[0,1,1]
	v_cvt_scalef32_pk_f32_fp4 v[164:165], v58, 1.0 op_sel:[0,1,0]
	v_pk_fma_f32 v[98:99], s[4:5], v[162:163], v[98:99] op_sel_hi:[0,1,1]
	v_cvt_scalef32_pk_f32_fp4 v[166:167], v58, 1.0 op_sel:[1,1,0]
	v_pk_fma_f32 v[96:97], s[4:5], v[164:165], v[96:97] op_sel_hi:[0,1,1]
	v_cvt_scalef32_pk_f32_fp4 v[168:169], v59, 1.0
	v_pk_fma_f32 v[94:95], s[4:5], v[166:167], v[94:95] op_sel_hi:[0,1,1]
	v_cvt_scalef32_pk_f32_fp4 v[170:171], v59, 1.0 op_sel:[1,0,0]
	v_pk_fma_f32 v[92:93], s[4:5], v[168:169], v[92:93] op_sel_hi:[0,1,1]
	v_cvt_scalef32_pk_f32_fp4 v[172:173], v59, 1.0 op_sel:[0,1,0]
	v_pk_fma_f32 v[90:91], s[4:5], v[170:171], v[90:91] op_sel_hi:[0,1,1]
	v_cvt_scalef32_pk_f32_fp4 v[174:175], v59, 1.0 op_sel:[1,1,0]
	v_pk_fma_f32 v[88:89], s[4:5], v[172:173], v[88:89] op_sel_hi:[0,1,1]
	v_pk_fma_f32 v[86:87], s[4:5], v[174:175], v[86:87] op_sel_hi:[0,1,1]
	global_load_dwordx2 v[58:59], v143, s[52:53]
	s_waitcnt vmcnt(15)
	v_readlane_b32 s4, v12, 16
	v_cvt_scalef32_pk_f32_fp4 v[160:161], v40, 1.0
	v_cvt_scalef32_pk_f32_fp4 v[162:163], v40, 1.0 op_sel:[1,0,0]
	v_pk_fma_f32 v[52:53], s[4:5], v[160:161], v[52:53] op_sel_hi:[0,1,1]
	v_cvt_scalef32_pk_f32_fp4 v[164:165], v40, 1.0 op_sel:[0,1,0]
	v_pk_fma_f32 v[50:51], s[4:5], v[162:163], v[50:51] op_sel_hi:[0,1,1]
	v_cvt_scalef32_pk_f32_fp4 v[166:167], v40, 1.0 op_sel:[1,1,0]
	v_pk_fma_f32 v[48:49], s[4:5], v[164:165], v[48:49] op_sel_hi:[0,1,1]
	v_cvt_scalef32_pk_f32_fp4 v[168:169], v41, 1.0
	v_pk_fma_f32 v[46:47], s[4:5], v[166:167], v[46:47] op_sel_hi:[0,1,1]
	v_cvt_scalef32_pk_f32_fp4 v[170:171], v41, 1.0 op_sel:[1,0,0]
	v_pk_fma_f32 v[44:45], s[4:5], v[168:169], v[44:45] op_sel_hi:[0,1,1]
	v_cvt_scalef32_pk_f32_fp4 v[172:173], v41, 1.0 op_sel:[0,1,0]
	v_pk_fma_f32 v[42:43], s[4:5], v[170:171], v[42:43] op_sel_hi:[0,1,1]
	v_cvt_scalef32_pk_f32_fp4 v[174:175], v41, 1.0 op_sel:[1,1,0]
	v_pk_fma_f32 v[54:55], s[4:5], v[172:173], v[54:55] op_sel_hi:[0,1,1]
	v_pk_fma_f32 v[56:57], s[4:5], v[174:175], v[56:57] op_sel_hi:[0,1,1]
	global_load_dwordx2 v[40:41], v144, s[52:53]
	s_waitcnt vmcnt(15)
	v_readlane_b32 s4, v12, 18
	v_cvt_scalef32_pk_f32_fp4 v[160:161], v38, 1.0
	v_cvt_scalef32_pk_f32_fp4 v[162:163], v38, 1.0 op_sel:[1,0,0]
	v_pk_fma_f32 v[52:53], s[4:5], v[160:161], v[52:53] op_sel_hi:[0,1,1]
	v_cvt_scalef32_pk_f32_fp4 v[164:165], v38, 1.0 op_sel:[0,1,0]
	v_pk_fma_f32 v[50:51], s[4:5], v[162:163], v[50:51] op_sel_hi:[0,1,1]
	v_cvt_scalef32_pk_f32_fp4 v[166:167], v38, 1.0 op_sel:[1,1,0]
	v_pk_fma_f32 v[48:49], s[4:5], v[164:165], v[48:49] op_sel_hi:[0,1,1]
	v_cvt_scalef32_pk_f32_fp4 v[168:169], v39, 1.0
	v_pk_fma_f32 v[46:47], s[4:5], v[166:167], v[46:47] op_sel_hi:[0,1,1]
	v_cvt_scalef32_pk_f32_fp4 v[170:171], v39, 1.0 op_sel:[1,0,0]
	v_pk_fma_f32 v[44:45], s[4:5], v[168:169], v[44:45] op_sel_hi:[0,1,1]
	v_cvt_scalef32_pk_f32_fp4 v[172:173], v39, 1.0 op_sel:[0,1,0]
	v_pk_fma_f32 v[42:43], s[4:5], v[170:171], v[42:43] op_sel_hi:[0,1,1]
	v_cvt_scalef32_pk_f32_fp4 v[174:175], v39, 1.0 op_sel:[1,1,0]
	v_pk_fma_f32 v[54:55], s[4:5], v[172:173], v[54:55] op_sel_hi:[0,1,1]
	v_pk_fma_f32 v[56:57], s[4:5], v[174:175], v[56:57] op_sel_hi:[0,1,1]
	global_load_dwordx2 v[38:39], v145, s[52:53]
	s_waitcnt vmcnt(15)
	v_readlane_b32 s4, v12, 17
	v_cvt_scalef32_pk_f32_fp4 v[160:161], v36, 1.0
	v_cvt_scalef32_pk_f32_fp4 v[162:163], v36, 1.0 op_sel:[1,0,0]
	v_pk_fma_f32 v[52:53], s[4:5], v[160:161], v[52:53] op_sel_hi:[0,1,1]
	v_cvt_scalef32_pk_f32_fp4 v[164:165], v36, 1.0 op_sel:[0,1,0]
	v_pk_fma_f32 v[50:51], s[4:5], v[162:163], v[50:51] op_sel_hi:[0,1,1]
	v_cvt_scalef32_pk_f32_fp4 v[166:167], v36, 1.0 op_sel:[1,1,0]
	v_pk_fma_f32 v[48:49], s[4:5], v[164:165], v[48:49] op_sel_hi:[0,1,1]
	v_cvt_scalef32_pk_f32_fp4 v[168:169], v37, 1.0
	v_pk_fma_f32 v[46:47], s[4:5], v[166:167], v[46:47] op_sel_hi:[0,1,1]
	v_cvt_scalef32_pk_f32_fp4 v[170:171], v37, 1.0 op_sel:[1,0,0]
	v_pk_fma_f32 v[44:45], s[4:5], v[168:169], v[44:45] op_sel_hi:[0,1,1]
	v_cvt_scalef32_pk_f32_fp4 v[172:173], v37, 1.0 op_sel:[0,1,0]
	v_pk_fma_f32 v[42:43], s[4:5], v[170:171], v[42:43] op_sel_hi:[0,1,1]
	v_cvt_scalef32_pk_f32_fp4 v[174:175], v37, 1.0 op_sel:[1,1,0]
	v_pk_fma_f32 v[54:55], s[4:5], v[172:173], v[54:55] op_sel_hi:[0,1,1]
	v_pk_fma_f32 v[56:57], s[4:5], v[174:175], v[56:57] op_sel_hi:[0,1,1]
	global_load_dwordx2 v[36:37], v146, s[52:53]
	s_waitcnt vmcnt(15)
	v_readlane_b32 s4, v12, 19
	v_cvt_scalef32_pk_f32_fp4 v[160:161], v34, 1.0
	v_cvt_scalef32_pk_f32_fp4 v[162:163], v34, 1.0 op_sel:[1,0,0]
	v_pk_fma_f32 v[52:53], s[4:5], v[160:161], v[52:53] op_sel_hi:[0,1,1]
	v_cvt_scalef32_pk_f32_fp4 v[164:165], v34, 1.0 op_sel:[0,1,0]
	v_pk_fma_f32 v[50:51], s[4:5], v[162:163], v[50:51] op_sel_hi:[0,1,1]
	v_cvt_scalef32_pk_f32_fp4 v[166:167], v34, 1.0 op_sel:[1,1,0]
	v_pk_fma_f32 v[48:49], s[4:5], v[164:165], v[48:49] op_sel_hi:[0,1,1]
	v_cvt_scalef32_pk_f32_fp4 v[168:169], v35, 1.0
	v_pk_fma_f32 v[46:47], s[4:5], v[166:167], v[46:47] op_sel_hi:[0,1,1]
	v_cvt_scalef32_pk_f32_fp4 v[170:171], v35, 1.0 op_sel:[1,0,0]
	v_pk_fma_f32 v[44:45], s[4:5], v[168:169], v[44:45] op_sel_hi:[0,1,1]
	v_cvt_scalef32_pk_f32_fp4 v[172:173], v35, 1.0 op_sel:[0,1,0]
	v_pk_fma_f32 v[42:43], s[4:5], v[170:171], v[42:43] op_sel_hi:[0,1,1]
	v_cvt_scalef32_pk_f32_fp4 v[174:175], v35, 1.0 op_sel:[1,1,0]
	v_pk_fma_f32 v[54:55], s[4:5], v[172:173], v[54:55] op_sel_hi:[0,1,1]
	v_pk_fma_f32 v[56:57], s[4:5], v[174:175], v[56:57] op_sel_hi:[0,1,1]
	global_load_dwordx2 v[34:35], v147, s[52:53]
	s_add_i32 s5, s5, 16
	s_cmpk_eq_i32 s5, 0x1f0
	s_cbranch_scc0 .LBB0_1075
; __device__ __forceinline__ void p3_dots(const u32x2 (&ur)[4], const unsigned* rec, int lane, int (&pt)[4]) {
;     const u32x4 qh = *(const u32x4*)(rec + 256 + lane * 4);
; #pragma unroll
;     for (int u = 0; u < 4; u++) {
;         const int w0 = (int)ur[u].x, w1 = (int)ur[u].y;
;         int dh = __builtin_amdgcn_sdot8(w0, (int)qh.x, 0, false);
;         dh = __builtin_amdgcn_sdot8(w1, (int)qh.z, dh, false);
;         int dl = __builtin_amdgcn_sdot8(w0, (int)qh.y, 0, false);
;         dl = __builtin_amdgcn_sdot8(w1, (int)qh.w, dl, false);
;         pt[u] = (dh << 4) + dl;
;     }
; }
; template <int CTRL> __device__ __forceinline__ int dpp_i(int v) { return __builtin_amdgcn_mov_dpp(v, CTRL, 0xF, 0xF, true); }
; __device__ __forceinline__ int xrow_sum_i(int v) {
;     const auto a = __builtin_amdgcn_permlane16_swap((unsigned)v, (unsigned)v, false, false);
;     v = (int)a[0] + (int)a[1];
;     const auto b = __builtin_amdgcn_permlane32_swap((unsigned)v, (unsigned)v, false, false);
;     return (int)b[0] + (int)b[1];
; }
; __device__ __forceinline__ float p3_weight(const int (&pt)[4], int lane, float sh, int hs8, const P3Sc& sc) {
;     int m2[2], m1;
;     const bool c0 = lane & 1;
; #pragma unroll
;     for (int j = 0; j < 2; j++) { const int keep = c0 ? pt[j + 2] : pt[j], send = c0 ? pt[j] : pt[j + 2]; m2[j] = keep + dpp_i<0xB1>(send); }
;     const bool c1 = lane & 2;
;     { const int keep = c1 ? m2[1] : m2[0], send = c1 ? m2[0] : m2[1]; m1 = keep + dpp_i<0x4E>(send); }
;     m1 += dpp_i<0x124>(m1);
;     m1 += dpp_i<0x128>(m1);
;     m1 = xrow_sum_i(m1);
;     const float aval = (float)(m1 - hs8) * sc.su;
;     return sc.gm * gelu_erf(aval);
; }
; __device__ __forceinline__ void p3_axpy(const u32x2 (&vr)[4], float ws, f32x2 (&acc)[8]) {
; #pragma unroll
;     for (int u = 0; u < 4; u++) {
;         const int la = ((u >> 1) & 1) | ((u & 1) << 1);
;         const float wu = __builtin_bit_cast(float, __builtin_amdgcn_readlane(__builtin_bit_cast(int, ws), la));
;         const f32x2 w2 = {wu, wu};
;         const unsigned vw[2] = {vr[u].x, vr[u].y};
; #pragma unroll
;         for (int i = 0; i < 2; i++) {
;             acc[i * 4 + 0] = __builtin_elementwise_fma(w2, __builtin_amdgcn_cvt_scalef32_pk_f32_fp4(vw[i], 1.0f, 0), acc[i * 4 + 0]);
	v_add_u32_e32 v135, 0x1e0, v120
	ds_read2st64_b32 v[104:105], v135 offset1:6
	ds_read2st64_b32 v[102:103], v135 offset0:10 offset1:16
	s_waitcnt vmcnt(0) lgkmcnt(0)
	v_mov_b32_e32 v12, v13
	v_mov_b32_e32 v27, v13
	s_waitcnt vmcnt(8)
	v_dot8c_i32_i4_e32 v12, v82, v4
	v_dot8c_i32_i4_e32 v27, v82, v5
	v_dot8c_i32_i4_e32 v12, v83, v6
	v_dot8c_i32_i4_e32 v27, v83, v7
	v_mov_b32_e32 v76, v13
	v_dot8c_i32_i4_e32 v76, v84, v5
	v_dot8c_i32_i4_e32 v76, v85, v7
	v_lshl_add_u32 v12, v12, 4, v27
	v_mov_b32_e32 v27, v13
	v_dot8c_i32_i4_e32 v27, v84, v4
	v_dot8c_i32_i4_e32 v27, v85, v6
	v_mov_b32_e32 v77, v13
	v_dot8c_i32_i4_e32 v77, v74, v5
	v_dot8c_i32_i4_e32 v77, v75, v7
	v_lshl_add_u32 v27, v27, 4, v76
	v_mov_b32_e32 v76, v13
	v_dot8c_i32_i4_e32 v76, v74, v4
	v_dot8c_i32_i4_e32 v76, v75, v6
	v_mov_b32_e32 v75, v13
	v_dot8c_i32_i4_e32 v75, v80, v4
	v_mov_b32_e32 v4, v13
	v_dot8c_i32_i4_e32 v4, v80, v5
	v_dot8c_i32_i4_e32 v75, v81, v6
	v_dot8c_i32_i4_e32 v4, v81, v7
	v_lshl_add_u32 v74, v76, 4, v77
	v_cndmask_b32_e64 v6, v74, v12, s[0:1]
	v_cvt_scalef32_pk_f32_fp4 v[76:77], v72, 1.0 op_sel:[1,1,0]
	v_lshl_add_u32 v4, v75, 4, v4
	v_cndmask_b32_e64 v5, v27, v4, s[0:1]
	v_cndmask_b32_e64 v4, v4, v27, s[0:1]
	v_cvt_scalef32_pk_f32_fp4 v[78:79], v73, 1.0
	v_cvt_scalef32_pk_f32_fp4 v[80:81], v73, 1.0 op_sel:[1,0,0]
	v_add_u32_dpp v4, v4, v5 quad_perm:[1,0,3,2] row_mask:0xf bank_mask:0xf bound_ctrl:1
	v_cndmask_b32_e64 v5, v12, v74, s[0:1]
	v_cvt_scalef32_pk_f32_fp4 v[74:75], v72, 1.0 op_sel:[0,1,0]
	v_cvt_scalef32_pk_f32_fp4 v[82:83], v73, 1.0 op_sel:[0,1,0]
	v_add_u32_dpp v5, v6, v5 quad_perm:[1,0,3,2] row_mask:0xf bank_mask:0xf bound_ctrl:1
	v_cndmask_b32_e64 v6, v5, v4, s[2:3]
	v_cndmask_b32_e64 v4, v4, v5, s[2:3]
	v_cvt_scalef32_pk_f32_fp4 v[84:85], v70, 1.0
	v_lshl_add_u64 v[28:29], v[22:23], 0, v[28:29]
	v_add_u32_dpp v4, v4, v6 quad_perm:[2,3,0,1] row_mask:0xf bank_mask:0xf bound_ctrl:1
	v_mov_b32_e32 v27, v13
	v_cvt_scalef32_pk_f32_fp4 v[108:109], v62, 1.0 op_sel:[0,1,0]
	v_add_u32_dpp v4, v4, v4 row_ror:4 row_mask:0xf bank_mask:0xf bound_ctrl:1
	s_nop 1
	v_add_u32_dpp v4, v4, v4 row_ror:8 row_mask:0xf bank_mask:0xf bound_ctrl:1
	v_mov_b32_e32 v5, v4
	s_nop 1
	v_permlane16_swap_b32_e32 v4, v5
	v_add_u32_e32 v4, v4, v5
	v_mov_b32_e32 v5, v4
	s_nop 1
	v_permlane32_swap_b32_e32 v4, v5
	v_add_u32_e32 v4, v5, v4
	v_cvt_f32_i32_e32 v4, v4
	v_mul_f32_e32 v4, v105, v4
	v_fma_f32 v5, |v4|, s39, 1.0
	v_rcp_f32_e32 v5, v5
	v_mul_f32_e32 v7, v4, v4
	v_mul_f32_e32 v7, 0xbf38aa3b, v7
	v_exp_f32_e32 v7, v7
	v_fmamk_f32 v6, v5, 0x3f07dc22, v129
	v_fmaak_f32 v6, v5, v6, 0x3f35f0e3
	v_fmaak_f32 v6, v5, v6, 0xbe11a98e
	v_fmaak_f32 v6, v5, v6, 0x3e027906
	v_mul_f32_e32 v5, v5, v6
	v_mul_f32_e32 v5, v7, v5
	v_mul_f32_e32 v6, v4, v5
	v_fma_f32 v5, -v4, v5, v4
	v_cmp_gt_f32_e32 vcc, 0, v4
	s_nop 1
	v_cndmask_b32_e32 v4, v5, v6, vcc
	v_mul_f32_e32 v12, v104, v4
	v_cvt_scalef32_pk_f32_fp4 v[4:5], v72, 1.0
	v_readlane_b32 s4, v12, 0
	v_cvt_scalef32_pk_f32_fp4 v[6:7], v72, 1.0 op_sel:[1,0,0]
	v_cvt_scalef32_pk_f32_fp4 v[72:73], v73, 1.0 op_sel:[1,1,0]
	v_pk_fma_f32 v[4:5], s[4:5], v[4:5], v[100:101] op_sel_hi:[0,1,1]
	v_pk_fma_f32 v[6:7], s[4:5], v[6:7], v[98:99] op_sel_hi:[0,1,1]
	v_pk_fma_f32 v[74:75], s[4:5], v[74:75], v[96:97] op_sel_hi:[0,1,1]
	v_pk_fma_f32 v[76:77], s[4:5], v[76:77], v[94:95] op_sel_hi:[0,1,1]
	v_pk_fma_f32 v[78:79], s[4:5], v[78:79], v[92:93] op_sel_hi:[0,1,1]
	v_pk_fma_f32 v[80:81], s[4:5], v[80:81], v[90:91] op_sel_hi:[0,1,1]
	v_pk_fma_f32 v[82:83], s[4:5], v[82:83], v[88:89] op_sel_hi:[0,1,1]
	v_pk_fma_f32 v[72:73], s[4:5], v[72:73], v[86:87] op_sel_hi:[0,1,1]
	v_readlane_b32 s4, v12, 2
	s_nop 1
	v_pk_fma_f32 v[4:5], s[4:5], v[84:85], v[4:5] op_sel_hi:[0,1,1]
	v_cvt_scalef32_pk_f32_fp4 v[84:85], v70, 1.0 op_sel:[1,0,0]
	v_pk_fma_f32 v[84:85], s[4:5], v[84:85], v[6:7] op_sel_hi:[0,1,1]
	v_cvt_scalef32_pk_f32_fp4 v[6:7], v70, 1.0 op_sel:[0,1,0]
	v_pk_fma_f32 v[90:91], s[4:5], v[6:7], v[74:75] op_sel_hi:[0,1,1]
	v_cvt_scalef32_pk_f32_fp4 v[6:7], v70, 1.0 op_sel:[1,1,0]
	v_pk_fma_f32 v[92:93], s[4:5], v[6:7], v[76:77] op_sel_hi:[0,1,1]
	v_cvt_scalef32_pk_f32_fp4 v[6:7], v71, 1.0
	v_pk_fma_f32 v[94:95], s[4:5], v[6:7], v[78:79] op_sel_hi:[0,1,1]
	v_cvt_scalef32_pk_f32_fp4 v[6:7], v71, 1.0 op_sel:[1,0,0]
	v_pk_fma_f32 v[96:97], s[4:5], v[6:7], v[80:81] op_sel_hi:[0,1,1]
	v_cvt_scalef32_pk_f32_fp4 v[6:7], v71, 1.0 op_sel:[0,1,0]
	v_pk_fma_f32 v[98:99], s[4:5], v[6:7], v[82:83] op_sel_hi:[0,1,1]
	v_cvt_scalef32_pk_f32_fp4 v[6:7], v71, 1.0 op_sel:[1,1,0]
	v_pk_fma_f32 v[100:101], s[4:5], v[6:7], v[72:73] op_sel_hi:[0,1,1]
	v_ashrrev_i32_e32 v6, 11, v8
	v_mul_i32_i24_e32 v6, 0x1800, v6
	v_ashrrev_i32_e32 v7, 31, v6
	v_lshl_add_u64 v[6:7], v[6:7], 2, s[22:23]
	v_readlane_b32 s4, v12, 1
	global_load_dwordx4 v[70:73], v[28:29], off offset:16
	global_load_dwordx4 v[74:77], v[28:29], off
	v_lshl_add_u64 v[28:29], v[6:7], 0, v[26:27]
	v_cvt_scalef32_pk_f32_fp4 v[82:83], v62, 1.0
	v_add_co_u32_e32 v6, vcc, s40, v28
	v_pk_fma_f32 v[104:105], s[4:5], v[82:83], v[4:5] op_sel_hi:[0,1,1]
	v_cvt_scalef32_pk_f32_fp4 v[4:5], v62, 1.0 op_sel:[1,0,0]
	v_addc_co_u32_e32 v7, vcc, 0, v29, vcc
	v_pk_fma_f32 v[106:107], s[4:5], v[4:5], v[84:85] op_sel_hi:[0,1,1]
	v_lshl_add_u64 v[4:5], v[28:29], 0, s[30:31]
	v_pk_fma_f32 v[28:29], s[4:5], v[108:109], v[90:91] op_sel_hi:[0,1,1]
	v_cvt_scalef32_pk_f32_fp4 v[90:91], v62, 1.0 op_sel:[1,1,0]
	v_pk_fma_f32 v[108:109], s[4:5], v[90:91], v[92:93] op_sel_hi:[0,1,1]
	v_cvt_scalef32_pk_f32_fp4 v[90:91], v63, 1.0
	global_load_dwordx4 v[78:81], v[6:7], off
	v_pk_fma_f32 v[94:95], s[4:5], v[90:91], v[94:95] op_sel_hi:[0,1,1]
	v_cvt_scalef32_pk_f32_fp4 v[90:91], v63, 1.0 op_sel:[1,0,0]
	global_load_dwordx4 v[82:85], v[4:5], off offset:32
	global_load_dwordx4 v[86:89], v[4:5], off offset:16
	v_pk_fma_f32 v[96:97], s[4:5], v[90:91], v[96:97] op_sel_hi:[0,1,1]
	v_cvt_scalef32_pk_f32_fp4 v[90:91], v63, 1.0 op_sel:[0,1,0]
	v_cvt_scalef32_pk_f32_fp4 v[62:63], v63, 1.0 op_sel:[1,1,0]
	v_pk_fma_f32 v[98:99], s[4:5], v[90:91], v[98:99] op_sel_hi:[0,1,1]
	v_pk_fma_f32 v[62:63], s[4:5], v[62:63], v[100:101] op_sel_hi:[0,1,1]
	v_readlane_b32 s4, v12, 3
	s_waitcnt vmcnt(11)
; __device__ __forceinline__ void p3_dots(const u32x2 (&ur)[4], const unsigned* rec, int lane, int (&pt)[4]) {
;     const u32x4 qh = *(const u32x4*)(rec + 256 + lane * 4);
; #pragma unroll
;     for (int u = 0; u < 4; u++) {
;         const int w0 = (int)ur[u].x, w1 = (int)ur[u].y;
;         int dh = __builtin_amdgcn_sdot8(w0, (int)qh.x, 0, false);
;         dh = __builtin_amdgcn_sdot8(w1, (int)qh.z, dh, false);
;         int dl = __builtin_amdgcn_sdot8(w0, (int)qh.y, 0, false);
;         dl = __builtin_amdgcn_sdot8(w1, (int)qh.w, dl, false);
;         pt[u] = (dh << 4) + dl;
;     }
; }
; template <int CTRL> __device__ __forceinline__ int dpp_i(int v) { return __builtin_amdgcn_mov_dpp(v, CTRL, 0xF, 0xF, true); }
; __device__ __forceinline__ int xrow_sum_i(int v) {
;     const auto a = __builtin_amdgcn_permlane16_swap((unsigned)v, (unsigned)v, false, false);
;     v = (int)a[0] + (int)a[1];
;     const auto b = __builtin_amdgcn_permlane32_swap((unsigned)v, (unsigned)v, false, false);
;     return (int)b[0] + (int)b[1];
; }
; __device__ __forceinline__ float p3_weight(const int (&pt)[4], int lane, float sh, int hs8, const P3Sc& sc) {
;     int m2[2], m1;
;     const bool c0 = lane & 1;
; #pragma unroll
;     for (int j = 0; j < 2; j++) { const int keep = c0 ? pt[j + 2] : pt[j], send = c0 ? pt[j] : pt[j + 2]; m2[j] = keep + dpp_i<0xB1>(send); }
;     const bool c1 = lane & 2;
;     { const int keep = c1 ? m2[1] : m2[0], send = c1 ? m2[0] : m2[1]; m1 = keep + dpp_i<0x4E>(send); }
;     m1 += dpp_i<0x124>(m1);
;     m1 += dpp_i<0x128>(m1);
;     m1 = xrow_sum_i(m1);
;     const float aval = (float)(m1 - hs8) * sc.su;
;     return sc.gm * gelu_erf(aval);
; }
; __device__ __forceinline__ void p3_finish(const Params& p, float* dstp, int tok, int lane, const f32x2 (&acc)[8], float* tr) {
;     const float* mod = (const float*)(p.ws + OFF_MOD);
;     const int b = tok >> 11;
;     float own[16];
; #pragma unroll
;     for (int i = 0; i < 16; i++) own[i] = acc[i >> 1][i & 1];
;     const int d0 = lane * 16;
;     float x2[16];
;     float ss = 0.f;
;     const bf16_t* x1b = (const bf16_t*)(p.ws + OFF_X1B) + (size_t)tok * DM + d0;
;     const u32x4 xa = *(const u32x4*)x1b, xb = *(const u32x4*)(x1b + 8);
;     const unsigned xw[8] = {xa.x, xa.y, xa.z, xa.w, xb.x, xb.y, xb.z, xb.w};
; #pragma unroll
;     for (int i = 0; i < 4; i++) {
	v_cvt_scalef32_pk_f32_fp4 v[90:91], v58, 1.0
	v_mov_b32_e32 v12, v13
	v_pk_fma_f32 v[100:101], s[4:5], v[90:91], v[104:105] op_sel_hi:[0,1,1]
	global_load_dwordx4 v[90:93], v[4:5], off offset:48
	v_cvt_scalef32_pk_f32_fp4 v[104:105], v58, 1.0 op_sel:[1,0,0]
	v_pk_fma_f32 v[104:105], s[4:5], v[104:105], v[106:107] op_sel_hi:[0,1,1]
	v_cvt_scalef32_pk_f32_fp4 v[106:107], v58, 1.0 op_sel:[0,1,0]
	v_pk_fma_f32 v[28:29], s[4:5], v[106:107], v[28:29] op_sel_hi:[0,1,1]
	v_cvt_scalef32_pk_f32_fp4 v[106:107], v58, 1.0 op_sel:[1,1,0]
	v_pk_fma_f32 v[106:107], s[4:5], v[106:107], v[108:109] op_sel_hi:[0,1,1]
	v_cvt_scalef32_pk_f32_fp4 v[108:109], v59, 1.0
	v_pk_fma_f32 v[94:95], s[4:5], v[108:109], v[94:95] op_sel_hi:[0,1,1]
	v_cvt_scalef32_pk_f32_fp4 v[108:109], v59, 1.0 op_sel:[1,0,0]
	s_waitcnt vmcnt(9)
	v_dot8c_i32_i4_e32 v12, v64, v0
	v_dot8c_i32_i4_e32 v27, v64, v1
	v_pk_fma_f32 v[96:97], s[4:5], v[108:109], v[96:97] op_sel_hi:[0,1,1]
	v_cvt_scalef32_pk_f32_fp4 v[108:109], v59, 1.0 op_sel:[0,1,0]
	v_cvt_scalef32_pk_f32_fp4 v[58:59], v59, 1.0 op_sel:[1,1,0]
	v_dot8c_i32_i4_e32 v12, v65, v2
	v_dot8c_i32_i4_e32 v27, v65, v3
	v_pk_fma_f32 v[98:99], s[4:5], v[108:109], v[98:99] op_sel_hi:[0,1,1]
	v_pk_fma_f32 v[108:109], s[4:5], v[58:59], v[62:63] op_sel_hi:[0,1,1]
	v_mov_b32_e32 v58, v13
	v_lshl_add_u32 v12, v12, 4, v27
	v_mov_b32_e32 v27, v13
	v_dot8c_i32_i4_e32 v27, v68, v0
	v_dot8c_i32_i4_e32 v58, v68, v1
	v_dot8c_i32_i4_e32 v27, v69, v2
	v_dot8c_i32_i4_e32 v58, v69, v3
	v_mov_b32_e32 v59, v13
	s_waitcnt vmcnt(7)
	v_dot8c_i32_i4_e32 v59, v60, v1
	v_dot8c_i32_i4_e32 v59, v61, v3
	v_lshl_add_u32 v27, v27, 4, v58
	v_mov_b32_e32 v58, v13
	v_dot8c_i32_i4_e32 v58, v60, v0
	v_dot8c_i32_i4_e32 v58, v61, v2
	s_waitcnt vmcnt(4)
	v_lshlrev_b32_e32 v110, 16, v74
	s_nop 0
	v_lshl_add_u32 v58, v58, 4, v59
	v_mov_b32_e32 v59, v13
	v_dot8c_i32_i4_e32 v59, v66, v0
	v_mov_b32_e32 v0, v13
	v_dot8c_i32_i4_e32 v0, v66, v1
	v_dot8c_i32_i4_e32 v59, v67, v2
	v_dot8c_i32_i4_e32 v0, v67, v3
	v_cndmask_b32_e64 v2, v58, v12, s[0:1]
	v_and_b32_e32 v111, 0xffff0000, v74
	v_lshlrev_b32_e32 v74, 16, v75
	v_lshl_add_u32 v0, v59, 4, v0
	v_cndmask_b32_e64 v1, v27, v0, s[0:1]
	v_cndmask_b32_e64 v0, v0, v27, s[0:1]
	v_and_b32_e32 v75, 0xffff0000, v75
	s_waitcnt vmcnt(3)
	v_pk_fma_f32 v[74:75], v[104:105], v[80:81], v[74:75]
	v_add_u32_dpp v0, v0, v1 quad_perm:[1,0,3,2] row_mask:0xf bank_mask:0xf bound_ctrl:1
	v_cndmask_b32_e64 v1, v12, v58, s[0:1]
	v_lshlrev_b32_e32 v104, 16, v76
	v_and_b32_e32 v105, 0xffff0000, v76
	v_add_u32_dpp v1, v2, v1 quad_perm:[1,0,3,2] row_mask:0xf bank_mask:0xf bound_ctrl:1
	v_cndmask_b32_e64 v12, v1, v0, s[2:3]
	v_cndmask_b32_e64 v27, v0, v1, s[2:3]
	global_load_dwordx4 v[0:3], v[24:25], off offset:48
	global_load_dwordx4 v[58:61], v[24:25], off offset:32
	global_load_dwordx4 v[62:65], v[24:25], off offset:16
	global_load_dwordx4 v[66:69], v[24:25], off
	v_pk_fma_f32 v[78:79], v[100:101], v[78:79], v[110:111]
	s_waitcnt vmcnt(5)
	v_pk_fma_f32 v[28:29], v[28:29], v[86:87], v[104:105]
	v_lshlrev_b32_e32 v104, 16, v70
	v_and_b32_e32 v105, 0xffff0000, v70
	v_lshlrev_b32_e32 v70, 16, v71
	v_and_b32_e32 v71, 0xffff0000, v71
	v_pk_mul_f32 v[100:101], v[78:79], v[78:79]
	v_pk_fma_f32 v[70:71], v[96:97], v[84:85], v[70:71]
	v_lshlrev_b32_e32 v96, 16, v72
	v_and_b32_e32 v97, 0xffff0000, v72
	v_pk_mul_f32 v[80:81], v[74:75], v[74:75]
	s_waitcnt vmcnt(4)
	v_pk_fma_f32 v[90:91], v[98:99], v[90:91], v[96:97]
	v_add_f32_e32 v98, v100, v101
	v_add_f32_e32 v80, v80, v98
	v_pk_mul_f32 v[86:87], v[28:29], v[28:29]
	v_lshlrev_b32_e32 v76, 16, v77
	v_and_b32_e32 v77, 0xffff0000, v77
	v_add_f32_e32 v80, v81, v80
	v_pk_fma_f32 v[76:77], v[106:107], v[88:89], v[76:77]
	v_add_f32_e32 v80, v86, v80
	v_pk_mul_f32 v[88:89], v[76:77], v[76:77]
	v_add_f32_e32 v80, v87, v80
	v_pk_fma_f32 v[82:83], v[94:95], v[82:83], v[104:105]
	v_add_f32_e32 v80, v88, v80
	v_pk_mul_f32 v[94:95], v[82:83], v[82:83]
	v_add_f32_e32 v80, v89, v80
	v_add_f32_e32 v80, v94, v80
	v_pk_mul_f32 v[84:85], v[70:71], v[70:71]
	v_add_f32_e32 v80, v95, v80
	v_add_f32_e32 v80, v84, v80
	v_pk_mul_f32 v[96:97], v[90:91], v[90:91]
	v_lshlrev_b32_e32 v72, 16, v73
	v_and_b32_e32 v73, 0xffff0000, v73
	v_add_f32_e32 v80, v85, v80
	v_pk_fma_f32 v[72:73], v[108:109], v[92:93], v[72:73]
	v_add_f32_e32 v80, v96, v80
	v_pk_mul_f32 v[92:93], v[72:73], v[72:73]
	v_add_f32_e32 v80, v97, v80
	v_add_f32_e32 v80, v92, v80
	v_add_f32_e32 v80, v93, v80
	ds_bpermute_b32 v81, v112, v80
	v_add_u32_dpp v12, v27, v12 quad_perm:[2,3,0,1] row_mask:0xf bank_mask:0xf bound_ctrl:1
	s_waitcnt lgkmcnt(0)
	v_add_f32_e32 v80, v80, v81
	ds_bpermute_b32 v81, v113, v80
	v_add_u32_dpp v12, v12, v12 row_ror:4 row_mask:0xf bank_mask:0xf bound_ctrl:1
	s_waitcnt lgkmcnt(0)
	v_add_f32_e32 v80, v80, v81
	v_add_u32_dpp v12, v12, v12 row_ror:8 row_mask:0xf bank_mask:0xf bound_ctrl:1
	v_mov_b32_e32 v27, v12
	ds_bpermute_b32 v81, v114, v80
	s_nop 0
	v_permlane16_swap_b32_e32 v12, v27
	v_add_u32_e32 v12, v12, v27
	v_mov_b32_e32 v27, v12
	s_nop 1
	v_permlane32_swap_b32_e32 v12, v27
	v_add_u32_e32 v12, v27, v12
	s_waitcnt lgkmcnt(0)
	v_add_f32_e32 v27, v80, v81
	ds_bpermute_b32 v80, v115, v27
	v_cvt_f32_i32_e32 v12, v12
	s_waitcnt lgkmcnt(0)
	v_add_f32_e32 v27, v27, v80
	ds_bpermute_b32 v80, v116, v27
	v_mul_f32_e32 v81, v103, v12
	v_fma_f32 v12, |v81|, s39, 1.0
	v_rcp_f32_e32 v12, v12
	s_waitcnt lgkmcnt(0)
	v_add_f32_e32 v27, v27, v80
	ds_bpermute_b32 v80, v117, v27
	v_fmamk_f32 v84, v12, 0x3f07dc22, v129
	v_fmaak_f32 v84, v12, v84, 0x3f35f0e3
	v_fmaak_f32 v84, v12, v84, 0xbe11a98e
	v_fmaak_f32 v84, v12, v84, 0x3e027906
	s_waitcnt lgkmcnt(0)
; __device__ __forceinline__ float p3_weight(const int (&pt)[4], int lane, float sh, int hs8, const P3Sc& sc) {
;     ...
;     const float aval = (float)(m1 - hs8) * sc.su;
;     return sc.gm * gelu_erf(aval);
; }
; __device__ __forceinline__ void p3_axpy(const u32x2 (&vr)[4], float ws, f32x2 (&acc)[8]) {
; #pragma unroll
;     for (int u = 0; u < 4; u++) {
;         const int la = ((u >> 1) & 1) | ((u & 1) << 1);
;         const float wu = __builtin_bit_cast(float, __builtin_amdgcn_readlane(__builtin_bit_cast(int, ws), la));
;         const f32x2 w2 = {wu, wu};
;         const unsigned vw[2] = {vr[u].x, vr[u].y};
; #pragma unroll
;         for (int i = 0; i < 2; i++) {
;             acc[i * 4 + 0] = __builtin_elementwise_fma(w2, __builtin_amdgcn_cvt_scalef32_pk_f32_fp4(vw[i], 1.0f, 0), acc[i * 4 + 0]);
;             acc[i * 4 + 1] = __builtin_elementwise_fma(w2, __builtin_amdgcn_cvt_scalef32_pk_f32_fp4(vw[i], 1.0f, 1), acc[i * 4 + 1]);
;             acc[i * 4 + 2] = __builtin_elementwise_fma(w2, __builtin_amdgcn_cvt_scalef32_pk_f32_fp4(vw[i], 1.0f, 2), acc[i * 4 + 2]);
;             acc[i * 4 + 3] = __builtin_elementwise_fma(w2, __builtin_amdgcn_cvt_scalef32_pk_f32_fp4(vw[i], 1.0f, 3), acc[i * 4 + 3]);
;         }
;     }
; }
; __device__ __forceinline__ void p3_finish(const Params& p, float* dstp, int tok, int lane, const f32x2 (&acc)[8], float* tr) {
;     ...
;     const float rstd = rsqrtf(ss * (1.f / 1024.f) + 1e-6f);
; #pragma unroll
;     for (int i = 0; i < 4; i++) {
;         const int d = d0 + i * 4;
;         const f32x4 fg = *(const f32x4*)(p.final_g + d);
;         f32x4 o;
; #pragma unroll
;         for (int j = 0; j < 4; j++) o[j] = x2[i * 4 + j] * rstd * fg[j];
;         *(f32x4*)(tr + d) = o;
;     }
;     __builtin_amdgcn_fence(__ATOMIC_RELEASE, "wavefront");
;     __builtin_amdgcn_wave_barrier();
;     __builtin_amdgcn_fence(__ATOMIC_ACQUIRE, "wavefront");
; #pragma unroll
;     for (int j = 0; j < 4; j++) {
;         const f32x4 v = *(const f32x4*)(tr + j * 256 + lane * 4);
;         *(f32x4*)(dstp + (size_t)tok * DM + j * 256 + lane * 4) = v;
;     }
;     __builtin_amdgcn_wave_barrier();
; }
	v_add_f32_e32 v27, v27, v80
	v_mul_f32_e32 v12, v12, v84
	v_mul_f32_e32 v84, v81, v81
	v_fmamk_f32 v27, v27, 0x3a800000, v130
	v_mul_f32_e32 v84, 0xbf38aa3b, v84
	v_mul_f32_e32 v80, 0x4b800000, v27
	v_cmp_gt_f32_e32 vcc, s38, v27
	v_exp_f32_e32 v84, v84
	s_nop 0
	v_cndmask_b32_e32 v27, v27, v80, vcc
	v_rsq_f32_e32 v27, v27
	v_mul_f32_e32 v12, v84, v12
	v_mul_f32_e32 v80, v81, v12
	v_fma_f32 v84, -v81, v12, v81
	v_mul_f32_e32 v12, 0x45800000, v27
	v_cndmask_b32_e32 v12, v27, v12, vcc
	v_pk_mul_f32 v[78:79], v[78:79], v[12:13] op_sel_hi:[1,0]
	v_pk_mul_f32 v[74:75], v[74:75], v[12:13] op_sel_hi:[1,0]
	s_waitcnt vmcnt(0)
	v_pk_mul_f32 v[66:67], v[66:67], v[78:79]
	v_pk_mul_f32 v[68:69], v[68:69], v[74:75]
	ds_write_b128 v118, v[66:69]
	v_pk_mul_f32 v[28:29], v[28:29], v[12:13] op_sel_hi:[1,0]
	v_pk_mul_f32 v[66:67], v[76:77], v[12:13] op_sel_hi:[1,0]
	v_pk_mul_f32 v[62:63], v[62:63], v[28:29]
	v_pk_mul_f32 v[64:65], v[64:65], v[66:67]
	ds_write_b128 v118, v[62:65] offset:16
	v_pk_mul_f32 v[28:29], v[82:83], v[12:13] op_sel_hi:[1,0]
	v_pk_mul_f32 v[62:63], v[70:71], v[12:13] op_sel_hi:[1,0]
	v_pk_mul_f32 v[58:59], v[58:59], v[28:29]
	v_pk_mul_f32 v[60:61], v[60:61], v[62:63]
	ds_write_b128 v118, v[58:61] offset:32
	v_pk_mul_f32 v[28:29], v[90:91], v[12:13] op_sel_hi:[1,0]
	v_pk_mul_f32 v[58:59], v[72:73], v[12:13] op_sel_hi:[1,0]
	v_pk_mul_f32 v[0:1], v[0:1], v[28:29]
	v_pk_mul_f32 v[2:3], v[2:3], v[58:59]
	ds_write_b128 v118, v[0:3] offset:48
	ds_read_b128 v[0:3], v128
	ds_read_b128 v[58:61], v128 offset:1024
	ds_read_b128 v[62:65], v128 offset:2048
	ds_read_b128 v[66:69], v128 offset:3072
	v_lshlrev_b64 v[28:29], 12, v[8:9]
	v_lshl_add_u64 v[28:29], v[18:19], 0, v[28:29]
	s_waitcnt lgkmcnt(3)
	global_store_dwordx4 v[28:29], v[0:3], off
	s_waitcnt lgkmcnt(2)
	global_store_dwordx4 v[28:29], v[58:61], off offset:1024
	s_waitcnt lgkmcnt(1)
	global_store_dwordx4 v[28:29], v[62:65], off offset:2048
	s_waitcnt lgkmcnt(0)
	global_store_dwordx4 v[28:29], v[66:69], off offset:3072
	v_lshl_add_u64 v[28:29], v[22:23], 0, v[32:33]
	global_load_dwordx4 v[0:3], v[28:29], off offset:16
	global_load_dwordx4 v[58:61], v[28:29], off
	global_load_dwordx4 v[62:65], v[6:7], off
	v_cmp_gt_f32_e32 vcc, 0, v81
	global_load_dwordx4 v[66:69], v[4:5], off offset:32
	global_load_dwordx4 v[70:73], v[4:5], off offset:16
	v_cndmask_b32_e32 v6, v84, v80, vcc
	v_mul_f32_e32 v9, v102, v6
	v_cvt_scalef32_pk_f32_fp4 v[6:7], v40, 1.0
	v_readlane_b32 s4, v9, 0
	v_add_u32_e32 v8, s36, v8
	s_waitcnt vmcnt(3)
	v_lshlrev_b32_e32 v78, 16, v58
	v_pk_fma_f32 v[28:29], s[4:5], v[6:7], v[52:53] op_sel_hi:[0,1,1]
	v_cvt_scalef32_pk_f32_fp4 v[6:7], v40, 1.0 op_sel:[1,0,0]
	v_pk_fma_f32 v[32:33], s[4:5], v[6:7], v[50:51] op_sel_hi:[0,1,1]
	v_cvt_scalef32_pk_f32_fp4 v[6:7], v40, 1.0 op_sel:[0,1,0]
	v_pk_fma_f32 v[48:49], s[4:5], v[6:7], v[48:49] op_sel_hi:[0,1,1]
	v_cvt_scalef32_pk_f32_fp4 v[6:7], v40, 1.0 op_sel:[1,1,0]
	v_pk_fma_f32 v[46:47], s[4:5], v[6:7], v[46:47] op_sel_hi:[0,1,1]
	v_cvt_scalef32_pk_f32_fp4 v[6:7], v41, 1.0
	v_pk_fma_f32 v[44:45], s[4:5], v[6:7], v[44:45] op_sel_hi:[0,1,1]
	v_cvt_scalef32_pk_f32_fp4 v[6:7], v41, 1.0 op_sel:[1,0,0]
	v_pk_fma_f32 v[42:43], s[4:5], v[6:7], v[42:43] op_sel_hi:[0,1,1]
	v_cvt_scalef32_pk_f32_fp4 v[6:7], v41, 1.0 op_sel:[0,1,0]
	v_pk_fma_f32 v[50:51], s[4:5], v[6:7], v[54:55] op_sel_hi:[0,1,1]
	v_cvt_scalef32_pk_f32_fp4 v[6:7], v41, 1.0 op_sel:[1,1,0]
	v_pk_fma_f32 v[40:41], s[4:5], v[6:7], v[56:57] op_sel_hi:[0,1,1]
	global_load_dwordx4 v[4:7], v[4:5], off offset:48
	v_readlane_b32 s4, v9, 2
	v_cvt_scalef32_pk_f32_fp4 v[52:53], v38, 1.0
	v_and_b32_e32 v79, 0xffff0000, v58
	v_pk_fma_f32 v[28:29], s[4:5], v[52:53], v[28:29] op_sel_hi:[0,1,1]
	v_cvt_scalef32_pk_f32_fp4 v[52:53], v38, 1.0 op_sel:[1,0,0]
	v_pk_fma_f32 v[32:33], s[4:5], v[52:53], v[32:33] op_sel_hi:[0,1,1]
	v_cvt_scalef32_pk_f32_fp4 v[52:53], v38, 1.0 op_sel:[0,1,0]
	v_pk_fma_f32 v[48:49], s[4:5], v[52:53], v[48:49] op_sel_hi:[0,1,1]
	v_cvt_scalef32_pk_f32_fp4 v[52:53], v38, 1.0 op_sel:[1,1,0]
	v_pk_fma_f32 v[46:47], s[4:5], v[52:53], v[46:47] op_sel_hi:[0,1,1]
	v_cvt_scalef32_pk_f32_fp4 v[52:53], v39, 1.0
	v_pk_fma_f32 v[44:45], s[4:5], v[52:53], v[44:45] op_sel_hi:[0,1,1]
	v_cvt_scalef32_pk_f32_fp4 v[52:53], v39, 1.0 op_sel:[1,0,0]
	v_pk_fma_f32 v[42:43], s[4:5], v[52:53], v[42:43] op_sel_hi:[0,1,1]
	v_cvt_scalef32_pk_f32_fp4 v[52:53], v39, 1.0 op_sel:[0,1,0]
	v_cvt_scalef32_pk_f32_fp4 v[38:39], v39, 1.0 op_sel:[1,1,0]
	v_pk_fma_f32 v[50:51], s[4:5], v[52:53], v[50:51] op_sel_hi:[0,1,1]
	v_pk_fma_f32 v[38:39], s[4:5], v[38:39], v[40:41] op_sel_hi:[0,1,1]
	v_readlane_b32 s4, v9, 1
	v_cvt_scalef32_pk_f32_fp4 v[40:41], v36, 1.0
	v_lshlrev_b32_e32 v58, 16, v59
	v_pk_fma_f32 v[28:29], s[4:5], v[40:41], v[28:29] op_sel_hi:[0,1,1]
	v_cvt_scalef32_pk_f32_fp4 v[40:41], v36, 1.0 op_sel:[1,0,0]
	v_pk_fma_f32 v[32:33], s[4:5], v[40:41], v[32:33] op_sel_hi:[0,1,1]
	v_cvt_scalef32_pk_f32_fp4 v[40:41], v36, 1.0 op_sel:[0,1,0]
	v_pk_fma_f32 v[40:41], s[4:5], v[40:41], v[48:49] op_sel_hi:[0,1,1]
	v_cvt_scalef32_pk_f32_fp4 v[48:49], v36, 1.0 op_sel:[1,1,0]
	v_pk_fma_f32 v[46:47], s[4:5], v[48:49], v[46:47] op_sel_hi:[0,1,1]
	v_cvt_scalef32_pk_f32_fp4 v[48:49], v37, 1.0
	v_pk_fma_f32 v[44:45], s[4:5], v[48:49], v[44:45] op_sel_hi:[0,1,1]
	v_cvt_scalef32_pk_f32_fp4 v[48:49], v37, 1.0 op_sel:[1,0,0]
	v_pk_fma_f32 v[42:43], s[4:5], v[48:49], v[42:43] op_sel_hi:[0,1,1]
	v_cvt_scalef32_pk_f32_fp4 v[48:49], v37, 1.0 op_sel:[0,1,0]
	v_cvt_scalef32_pk_f32_fp4 v[36:37], v37, 1.0 op_sel:[1,1,0]
	v_pk_fma_f32 v[48:49], s[4:5], v[48:49], v[50:51] op_sel_hi:[0,1,1]
	v_pk_fma_f32 v[36:37], s[4:5], v[36:37], v[38:39] op_sel_hi:[0,1,1]
	v_readlane_b32 s4, v9, 3
	v_cvt_scalef32_pk_f32_fp4 v[38:39], v34, 1.0
	v_and_b32_e32 v59, 0xffff0000, v59
	v_pk_fma_f32 v[28:29], s[4:5], v[38:39], v[28:29] op_sel_hi:[0,1,1]
	v_cvt_scalef32_pk_f32_fp4 v[38:39], v34, 1.0 op_sel:[1,0,0]
	v_pk_fma_f32 v[50:51], s[4:5], v[38:39], v[32:33] op_sel_hi:[0,1,1]
	v_cvt_scalef32_pk_f32_fp4 v[32:33], v34, 1.0 op_sel:[0,1,0]
	v_pk_fma_f32 v[52:53], s[4:5], v[32:33], v[40:41] op_sel_hi:[0,1,1]
	v_cvt_scalef32_pk_f32_fp4 v[32:33], v34, 1.0 op_sel:[1,1,0]
	v_pk_fma_f32 v[54:55], s[4:5], v[32:33], v[46:47] op_sel_hi:[0,1,1]
	v_cvt_scalef32_pk_f32_fp4 v[32:33], v35, 1.0
	v_pk_fma_f32 v[56:57], s[4:5], v[32:33], v[44:45] op_sel_hi:[0,1,1]
	v_cvt_scalef32_pk_f32_fp4 v[32:33], v35, 1.0 op_sel:[1,0,0]
	v_pk_fma_f32 v[74:75], s[4:5], v[32:33], v[42:43] op_sel_hi:[0,1,1]
	v_cvt_scalef32_pk_f32_fp4 v[32:33], v35, 1.0 op_sel:[0,1,0]
	v_pk_fma_f32 v[48:49], s[4:5], v[32:33], v[48:49] op_sel_hi:[0,1,1]
	v_cvt_scalef32_pk_f32_fp4 v[32:33], v35, 1.0 op_sel:[1,1,0]
	v_pk_fma_f32 v[76:77], s[4:5], v[32:33], v[36:37] op_sel_hi:[0,1,1]
	global_load_dwordx4 v[32:35], v[24:25], off offset:48
	global_load_dwordx4 v[36:39], v[24:25], off offset:32
	global_load_dwordx4 v[40:43], v[24:25], off offset:16
	global_load_dwordx4 v[44:47], v[24:25], off
	s_waitcnt vmcnt(7)
; __device__ __forceinline__ float bf_lo(unsigned u) { return __uint_as_float(u << 16); }
; __device__ __forceinline__ float bf_hi(unsigned u) { return __uint_as_float(u & 0xffff0000u); }
; __device__ __forceinline__ int vblk() { return (int)blockIdx.x * 2 + half_id(); }
; __device__ __forceinline__ int vgrid() { return (int)gridDim.x * 2; }
; __device__ __forceinline__ void p3_finish(const Params& p, float* dstp, int tok, int lane, const f32x2 (&acc)[8], float* tr) {
;     ...
;     for (int i = 0; i < 4; i++) {
;         const int d = d0 + i * 4;
;         const f32x4 xv = {bf_lo(xw[2 * i]), bf_hi(xw[2 * i]), bf_lo(xw[2 * i + 1]), bf_hi(xw[2 * i + 1])};
;         const f32x4 gt = *(const f32x4*)(mod + b * 6144 + 5 * 1024 + d);
; #pragma unroll
;         for (int j = 0; j < 4; j++) { const float v = xv[j] + gt[j] * own[i * 4 + j]; x2[i * 4 + j] = v; ss += v * v; }
;     }
;     ss = wave_sum(ss);
;     const float rstd = rsqrtf(ss * (1.f / 1024.f) + 1e-6f);
; #pragma unroll
;     for (int i = 0; i < 4; i++) {
;         const int d = d0 + i * 4;
;         const f32x4 fg = *(const f32x4*)(p.final_g + d);
;         f32x4 o;
; #pragma unroll
;         for (int j = 0; j < 4; j++) o[j] = x2[i * 4 + j] * rstd * fg[j];
;         *(f32x4*)(tr + d) = o;
;     }
;     __builtin_amdgcn_fence(__ATOMIC_RELEASE, "wavefront");
;     __builtin_amdgcn_wave_barrier();
;     __builtin_amdgcn_fence(__ATOMIC_ACQUIRE, "wavefront");
; #pragma unroll
;     for (int j = 0; j < 4; j++) {
;         const f32x4 v = *(const f32x4*)(tr + j * 256 + lane * 4);
;         *(f32x4*)(dstp + (size_t)tok * DM + j * 256 + lane * 4) = v;
;     }
;     __builtin_amdgcn_wave_barrier();
; }
; __device__ void phaseP3(const Params& p, float* dstp, char* lds) {
;     ...
;     for (int tb = (vblk() * 4 + wave) * TPW; tb < NTOK; tb += vgrid() * 4 * TPW) {
	v_pk_fma_f32 v[28:29], v[28:29], v[62:63], v[78:79]
	v_pk_fma_f32 v[50:51], v[50:51], v[64:65], v[58:59]
	v_pk_mul_f32 v[62:63], v[28:29], v[28:29]
	v_pk_mul_f32 v[58:59], v[50:51], v[50:51]
	v_lshlrev_b32_e32 v64, 16, v60
	v_and_b32_e32 v65, 0xffff0000, v60
	v_add_f32_e32 v9, v62, v63
	s_waitcnt vmcnt(5)
	v_pk_fma_f32 v[52:53], v[52:53], v[70:71], v[64:65]
	v_add_f32_e32 v9, v58, v9
	v_pk_mul_f32 v[64:65], v[52:53], v[52:53]
	v_lshlrev_b32_e32 v60, 16, v61
	v_and_b32_e32 v61, 0xffff0000, v61
	v_add_f32_e32 v9, v59, v9
	v_pk_fma_f32 v[54:55], v[54:55], v[72:73], v[60:61]
	v_add_f32_e32 v9, v64, v9
	v_pk_mul_f32 v[60:61], v[54:55], v[54:55]
	v_lshlrev_b32_e32 v70, 16, v0
	v_and_b32_e32 v71, 0xffff0000, v0
	v_add_f32_e32 v9, v65, v9
	v_pk_fma_f32 v[56:57], v[56:57], v[66:67], v[70:71]
	v_add_f32_e32 v9, v60, v9
	v_pk_mul_f32 v[66:67], v[56:57], v[56:57]
	v_lshlrev_b32_e32 v0, 16, v1
	v_and_b32_e32 v1, 0xffff0000, v1
	v_add_f32_e32 v9, v61, v9
	v_pk_fma_f32 v[68:69], v[74:75], v[68:69], v[0:1]
	v_add_f32_e32 v9, v66, v9
	v_pk_mul_f32 v[0:1], v[68:69], v[68:69]
	v_lshlrev_b32_e32 v70, 16, v2
	v_and_b32_e32 v71, 0xffff0000, v2
	v_add_f32_e32 v9, v67, v9
	s_waitcnt vmcnt(4)
	v_pk_fma_f32 v[4:5], v[48:49], v[4:5], v[70:71]
	v_add_f32_e32 v0, v0, v9
	v_pk_mul_f32 v[48:49], v[4:5], v[4:5]
	v_lshlrev_b32_e32 v2, 16, v3
	v_and_b32_e32 v3, 0xffff0000, v3
	v_add_f32_e32 v0, v1, v0
	v_pk_fma_f32 v[6:7], v[76:77], v[6:7], v[2:3]
	v_add_f32_e32 v0, v48, v0
	v_pk_mul_f32 v[2:3], v[6:7], v[6:7]
	v_add_f32_e32 v0, v49, v0
	v_add_f32_e32 v0, v2, v0
	v_add_f32_e32 v0, v3, v0
	ds_bpermute_b32 v1, v112, v0
	s_waitcnt lgkmcnt(0)
	v_add_f32_e32 v0, v0, v1
	ds_bpermute_b32 v1, v113, v0
	s_waitcnt lgkmcnt(0)
	v_add_f32_e32 v0, v0, v1
	ds_bpermute_b32 v1, v114, v0
	s_waitcnt lgkmcnt(0)
	v_add_f32_e32 v0, v0, v1
	ds_bpermute_b32 v1, v115, v0
	s_waitcnt lgkmcnt(0)
	v_add_f32_e32 v0, v0, v1
	ds_bpermute_b32 v1, v116, v0
	s_waitcnt lgkmcnt(0)
	v_add_f32_e32 v0, v0, v1
	ds_bpermute_b32 v1, v117, v0
	s_waitcnt lgkmcnt(0)
	v_add_f32_e32 v0, v0, v1
	v_fmamk_f32 v0, v0, 0x3a800000, v130
	v_mul_f32_e32 v1, 0x4b800000, v0
	v_cmp_gt_f32_e32 vcc, s38, v0
	s_nop 1
	v_cndmask_b32_e32 v0, v0, v1, vcc
	v_rsq_f32_e32 v0, v0
	s_nop 0
	v_mul_f32_e32 v1, 0x45800000, v0
	v_cndmask_b32_e32 v12, v0, v1, vcc
	v_pk_mul_f32 v[0:1], v[28:29], v[12:13] op_sel_hi:[1,0]
	v_pk_mul_f32 v[2:3], v[50:51], v[12:13] op_sel_hi:[1,0]
	s_waitcnt vmcnt(0)
	v_pk_mul_f32 v[0:1], v[44:45], v[0:1]
	v_pk_mul_f32 v[2:3], v[46:47], v[2:3]
	ds_write_b128 v118, v[0:3]
	v_pk_mul_f32 v[0:1], v[52:53], v[12:13] op_sel_hi:[1,0]
	v_pk_mul_f32 v[2:3], v[54:55], v[12:13] op_sel_hi:[1,0]
	v_pk_mul_f32 v[0:1], v[40:41], v[0:1]
	v_pk_mul_f32 v[2:3], v[42:43], v[2:3]
	ds_write_b128 v118, v[0:3] offset:16
	v_pk_mul_f32 v[0:1], v[56:57], v[12:13] op_sel_hi:[1,0]
	v_pk_mul_f32 v[2:3], v[68:69], v[12:13] op_sel_hi:[1,0]
	v_pk_mul_f32 v[0:1], v[36:37], v[0:1]
	v_pk_mul_f32 v[2:3], v[38:39], v[2:3]
	ds_write_b128 v118, v[0:3] offset:32
	v_pk_mul_f32 v[0:1], v[4:5], v[12:13] op_sel_hi:[1,0]
	v_pk_mul_f32 v[2:3], v[6:7], v[12:13] op_sel_hi:[1,0]
	v_pk_mul_f32 v[0:1], v[32:33], v[0:1]
	v_pk_mul_f32 v[2:3], v[34:35], v[2:3]
	ds_write_b128 v118, v[0:3] offset:48
	ds_read_b128 v[0:3], v128
	ds_read_b128 v[4:7], v128 offset:1024
	v_lshlrev_b64 v[32:33], 12, v[30:31]
	v_lshl_add_u64 v[32:33], v[18:19], 0, v[32:33]
	ds_read_b128 v[28:31], v128 offset:2048
	s_waitcnt lgkmcnt(2)
	global_store_dwordx4 v[32:33], v[0:3], off
	s_waitcnt lgkmcnt(1)
	global_store_dwordx4 v[32:33], v[4:7], off offset:1024
	ds_read_b128 v[0:3], v128 offset:3072
	v_cmp_lt_i32_e32 vcc, s41, v8
	s_or_b64 s[28:29], vcc, s[28:29]
	s_waitcnt lgkmcnt(1)
	global_store_dwordx4 v[32:33], v[28:31], off offset:2048
	s_waitcnt lgkmcnt(0)
	global_store_dwordx4 v[32:33], v[0:3], off offset:3072
	s_andn2_b64 exec, exec, s[28:29]
	s_cbranch_execnz .LBB0_1042
